# GEMM loops: set-up instructions between a phase's last MFMA and its trailing barrier moved behind the barrier; duplicate lgkmcnt(0) dropped
# speedup vs baseline: 1.0054x; 1.0054x over previous
.LBB0_37:
	s_add_i32 s69, s48, 2
	s_add_u32 s46, s0, 0x100
	s_addc_u32 s47, s1, 0
	s_add_i32 s70, 0, 0x10000
	v_add_u32_e32 v156, s70, v153
	ds_read_b128 v[140:143], v156
	ds_read_b128 v[144:147], v156 offset:1024
	ds_read_b128 v[148:151], v156 offset:2048
	ds_read_b128 v[168:171], v156 offset:3072
	s_cmp_eq_u32 s12, s48
	s_cselect_b32 s48, s44, s13
	s_cselect_b32 s51, s43, s47
	s_cselect_b32 s50, s42, s46
	s_cselect_b32 s49, s45, s68
	v_lshl_add_u64 v[156:157], s[0:1], 0, v[136:137]
	s_add_i32 m0, s53, 0xc000
	ds_read_b128 v[172:175], v155
	ds_read_b128 v[176:179], v155 offset:1024
	ds_read_b128 v[180:183], v155 offset:2048
	ds_read_b128 v[184:187], v155 offset:3072
	ds_read_b128 v[188:191], v155 offset:4096
	ds_read_b128 v[192:195], v155 offset:5120
	ds_read_b128 v[196:199], v155 offset:6144
	ds_read_b128 v[224:227], v155 offset:7168
	global_load_lds_dwordx4 v[156:157], off
	v_lshl_add_u64 v[156:157], s[0:1], 0, v[138:139]
	s_add_i32 m0, s53, 0xe000
	s_nop 0
	global_load_lds_dwordx4 v[156:157], off
	s_waitcnt lgkmcnt(8)
	s_barrier
	s_waitcnt lgkmcnt(0)
	v_mfma_f32_16x16x32_bf16 v[126:129], v[140:143], v[172:175], v[126:129]
	v_mfma_f32_16x16x32_bf16 v[122:125], v[148:151], v[172:175], v[122:125]
	v_mfma_f32_16x16x32_bf16 v[110:113], v[140:143], v[180:183], v[110:113]
	v_mfma_f32_16x16x32_bf16 v[106:109], v[148:151], v[180:183], v[106:109]
	v_mfma_f32_16x16x32_bf16 v[94:97], v[140:143], v[188:191], v[94:97]
	v_mfma_f32_16x16x32_bf16 v[90:93], v[148:151], v[188:191], v[90:93]
	v_mfma_f32_16x16x32_bf16 v[78:81], v[140:143], v[196:199], v[78:81]
	v_mfma_f32_16x16x32_bf16 v[74:77], v[148:151], v[196:199], v[74:77]
	v_mfma_f32_16x16x32_bf16 v[126:129], v[144:147], v[176:179], v[126:129]
	v_mfma_f32_16x16x32_bf16 v[122:125], v[168:171], v[176:179], v[122:125]
	v_mfma_f32_16x16x32_bf16 v[110:113], v[144:147], v[184:187], v[110:113]
	v_mfma_f32_16x16x32_bf16 v[106:109], v[168:171], v[184:187], v[106:109]
	v_mfma_f32_16x16x32_bf16 v[94:97], v[144:147], v[192:195], v[94:97]
	v_mfma_f32_16x16x32_bf16 v[90:93], v[168:171], v[192:195], v[90:93]
	v_mfma_f32_16x16x32_bf16 v[78:81], v[144:147], v[224:227], v[78:81]
	v_mfma_f32_16x16x32_bf16 v[74:77], v[168:171], v[224:227], v[74:77]
	s_barrier
	s_add_i32 s71, 0, 0x14000
	v_add_u32_e32 v156, s71, v153
	s_add_i32 s0, s70, s52
	ds_read_b128 v[228:231], v156
	ds_read_b128 v[232:235], v156 offset:1024
	ds_read_b128 v[236:239], v156 offset:2048
	ds_read_b128 v[240:243], v156 offset:3072
	s_add_u32 s76, s48, s94
	s_addc_u32 s77, s49, s95
	s_mov_b32 m0, s0
	s_nop 0
	global_load_lds_dwordx4 v0, s[48:49]
	s_add_i32 m0, s0, 0x2000
	s_nop 0
	global_load_lds_dwordx4 v130, s[48:49]
	s_barrier
	s_waitcnt lgkmcnt(0)
	v_mfma_f32_16x16x32_bf16 v[118:121], v[228:231], v[172:175], v[118:121]
	v_mfma_f32_16x16x32_bf16 v[114:117], v[236:239], v[172:175], v[114:117]
	v_mfma_f32_16x16x32_bf16 v[102:105], v[228:231], v[180:183], v[102:105]
	v_mfma_f32_16x16x32_bf16 v[98:101], v[236:239], v[180:183], v[98:101]
	v_mfma_f32_16x16x32_bf16 v[86:89], v[228:231], v[188:191], v[86:89]
	v_mfma_f32_16x16x32_bf16 v[82:85], v[236:239], v[188:191], v[82:85]
	v_mfma_f32_16x16x32_bf16 v[70:73], v[228:231], v[196:199], v[70:73]
	v_mfma_f32_16x16x32_bf16 v[66:69], v[236:239], v[196:199], v[66:69]
	v_mfma_f32_16x16x32_bf16 v[118:121], v[232:235], v[176:179], v[118:121]
	v_mfma_f32_16x16x32_bf16 v[114:117], v[240:243], v[176:179], v[114:117]
	v_mfma_f32_16x16x32_bf16 v[102:105], v[232:235], v[184:187], v[102:105]
	v_mfma_f32_16x16x32_bf16 v[98:101], v[240:243], v[184:187], v[98:101]
	v_mfma_f32_16x16x32_bf16 v[86:89], v[232:235], v[192:195], v[86:89]
	v_mfma_f32_16x16x32_bf16 v[82:85], v[240:243], v[192:195], v[82:85]
	v_mfma_f32_16x16x32_bf16 v[70:73], v[232:235], v[224:227], v[70:73]
	v_mfma_f32_16x16x32_bf16 v[66:69], v[240:243], v[224:227], v[66:69]
	s_barrier
	s_mov_b32 m0, s53
	s_add_u32 s78, s50, s94
	s_addc_u32 s79, s51, s95
	ds_read_b128 v[172:175], v155 offset:16384
	ds_read_b128 v[176:179], v155 offset:17408
	ds_read_b128 v[180:183], v155 offset:18432
	ds_read_b128 v[184:187], v155 offset:19456
	ds_read_b128 v[188:191], v155 offset:20480
	ds_read_b128 v[192:195], v155 offset:21504
	ds_read_b128 v[196:199], v155 offset:22528
	ds_read_b128 v[224:227], v155 offset:23552
	global_load_lds_dwordx4 v134, s[50:51]
	s_mov_b32 m0, s54
	s_nop 0
	global_load_lds_dwordx4 v132, s[50:51]
	s_barrier
	s_waitcnt lgkmcnt(0)
	v_mfma_f32_16x16x32_bf16 v[62:65], v[140:143], v[172:175], v[62:65]
	v_mfma_f32_16x16x32_bf16 v[58:61], v[148:151], v[172:175], v[58:61]
	v_mfma_f32_16x16x32_bf16 v[46:49], v[140:143], v[180:183], v[46:49]
	v_mfma_f32_16x16x32_bf16 v[42:45], v[148:151], v[180:183], v[42:45]
	v_mfma_f32_16x16x32_bf16 v[30:33], v[140:143], v[188:191], v[30:33]
	v_mfma_f32_16x16x32_bf16 v[26:29], v[148:151], v[188:191], v[26:29]
	v_mfma_f32_16x16x32_bf16 v[14:17], v[140:143], v[196:199], v[14:17]
	v_mfma_f32_16x16x32_bf16 v[10:13], v[148:151], v[196:199], v[10:13]
	v_mfma_f32_16x16x32_bf16 v[62:65], v[144:147], v[176:179], v[62:65]
	v_mfma_f32_16x16x32_bf16 v[58:61], v[168:171], v[176:179], v[58:61]
	v_mfma_f32_16x16x32_bf16 v[46:49], v[144:147], v[184:187], v[46:49]
	v_mfma_f32_16x16x32_bf16 v[42:45], v[168:171], v[184:187], v[42:45]
	v_mfma_f32_16x16x32_bf16 v[30:33], v[144:147], v[192:195], v[30:33]
	v_mfma_f32_16x16x32_bf16 v[26:29], v[168:171], v[192:195], v[26:29]
	v_mfma_f32_16x16x32_bf16 v[14:17], v[144:147], v[224:227], v[14:17]
	v_mfma_f32_16x16x32_bf16 v[10:13], v[168:171], v[224:227], v[10:13]
	s_barrier
	s_add_u32 s0, s48, 0x160000
	s_addc_u32 s1, s49, 0
	s_add_i32 s70, s71, s52
	s_mov_b32 m0, s70
	s_nop 0
	global_load_lds_dwordx4 v0, s[0:1]
	s_add_i32 m0, s70, 0x2000
	s_nop 0
	global_load_lds_dwordx4 v130, s[0:1]
	s_waitcnt vmcnt(6)
	s_barrier
	v_mfma_f32_16x16x32_bf16 v[54:57], v[228:231], v[172:175], v[54:57]
	v_mfma_f32_16x16x32_bf16 v[50:53], v[236:239], v[172:175], v[50:53]
	v_mfma_f32_16x16x32_bf16 v[38:41], v[228:231], v[180:183], v[38:41]
	v_mfma_f32_16x16x32_bf16 v[34:37], v[236:239], v[180:183], v[34:37]
	v_mfma_f32_16x16x32_bf16 v[22:25], v[228:231], v[188:191], v[22:25]
	v_mfma_f32_16x16x32_bf16 v[18:21], v[236:239], v[188:191], v[18:21]
	v_mfma_f32_16x16x32_bf16 v[6:9], v[228:231], v[196:199], v[6:9]
	v_mfma_f32_16x16x32_bf16 v[2:5], v[236:239], v[196:199], v[2:5]
	v_mfma_f32_16x16x32_bf16 v[54:57], v[232:235], v[176:179], v[54:57]
	v_mfma_f32_16x16x32_bf16 v[50:53], v[240:243], v[176:179], v[50:53]
	v_mfma_f32_16x16x32_bf16 v[38:41], v[232:235], v[184:187], v[38:41]
	v_mfma_f32_16x16x32_bf16 v[34:37], v[240:243], v[184:187], v[34:37]
	v_mfma_f32_16x16x32_bf16 v[22:25], v[232:235], v[192:195], v[22:25]
	v_mfma_f32_16x16x32_bf16 v[18:21], v[240:243], v[192:195], v[18:21]
	v_mfma_f32_16x16x32_bf16 v[6:9], v[232:235], v[224:227], v[6:9]
	v_mfma_f32_16x16x32_bf16 v[2:5], v[240:243], v[224:227], v[2:5]
	s_barrier
	s_add_i32 s70, 0, 0x18000
	v_add_u32_e32 v161, s70, v153
	ds_read_b128 v[140:143], v161
	ds_read_b128 v[144:147], v161 offset:1024
	ds_read_b128 v[148:151], v161 offset:2048
	ds_read_b128 v[168:171], v161 offset:3072
	s_add_u32 s0, s50, 0x2c0000
	s_addc_u32 s1, s51, 0
	s_mov_b32 m0, s55
	ds_read_b128 v[172:175], v155 offset:32768
	ds_read_b128 v[176:179], v155 offset:33792
	ds_read_b128 v[180:183], v155 offset:34816
	ds_read_b128 v[184:187], v155 offset:35840
	ds_read_b128 v[188:191], v155 offset:36864
	ds_read_b128 v[192:195], v155 offset:37888
	ds_read_b128 v[196:199], v155 offset:38912
	ds_read_b128 v[224:227], v155 offset:39936
	global_load_lds_dwordx4 v134, s[0:1]
	s_mov_b32 m0, s56
	s_nop 0
	global_load_lds_dwordx4 v132, s[0:1]
	s_waitcnt lgkmcnt(8)
	s_barrier
	s_waitcnt lgkmcnt(0)
	v_mfma_f32_16x16x32_bf16 v[126:129], v[140:143], v[172:175], v[126:129]
	v_mfma_f32_16x16x32_bf16 v[122:125], v[148:151], v[172:175], v[122:125]
	v_mfma_f32_16x16x32_bf16 v[110:113], v[140:143], v[180:183], v[110:113]
	v_mfma_f32_16x16x32_bf16 v[106:109], v[148:151], v[180:183], v[106:109]
	v_mfma_f32_16x16x32_bf16 v[94:97], v[140:143], v[188:191], v[94:97]
	v_mfma_f32_16x16x32_bf16 v[90:93], v[148:151], v[188:191], v[90:93]
	v_mfma_f32_16x16x32_bf16 v[78:81], v[140:143], v[196:199], v[78:81]
	v_mfma_f32_16x16x32_bf16 v[74:77], v[148:151], v[196:199], v[74:77]
	v_mfma_f32_16x16x32_bf16 v[126:129], v[144:147], v[176:179], v[126:129]
	v_mfma_f32_16x16x32_bf16 v[122:125], v[168:171], v[176:179], v[122:125]
	v_mfma_f32_16x16x32_bf16 v[110:113], v[144:147], v[184:187], v[110:113]
	v_mfma_f32_16x16x32_bf16 v[106:109], v[168:171], v[184:187], v[106:109]
	v_mfma_f32_16x16x32_bf16 v[94:97], v[144:147], v[192:195], v[94:97]
	v_mfma_f32_16x16x32_bf16 v[90:93], v[168:171], v[192:195], v[90:93]
	v_mfma_f32_16x16x32_bf16 v[78:81], v[144:147], v[224:227], v[78:81]
	v_mfma_f32_16x16x32_bf16 v[74:77], v[168:171], v[224:227], v[74:77]
	s_barrier
	s_add_i32 s50, 0, 0x1c000
	s_add_i32 s0, s70, s52
	v_add_u32_e32 v161, s50, v153
	s_mov_b32 m0, s0
	ds_read_b128 v[228:231], v161
	ds_read_b128 v[232:235], v161 offset:1024
	ds_read_b128 v[236:239], v161 offset:2048
	ds_read_b128 v[240:243], v161 offset:3072
	global_load_lds_dwordx4 v0, s[76:77]
	s_add_i32 m0, s0, 0x2000
	s_nop 0
	global_load_lds_dwordx4 v130, s[76:77]
	s_barrier
	s_waitcnt lgkmcnt(0)
	v_mfma_f32_16x16x32_bf16 v[118:121], v[228:231], v[172:175], v[118:121]
	v_mfma_f32_16x16x32_bf16 v[114:117], v[236:239], v[172:175], v[114:117]
	v_mfma_f32_16x16x32_bf16 v[102:105], v[228:231], v[180:183], v[102:105]
	v_mfma_f32_16x16x32_bf16 v[98:101], v[236:239], v[180:183], v[98:101]
	v_mfma_f32_16x16x32_bf16 v[86:89], v[228:231], v[188:191], v[86:89]
	v_mfma_f32_16x16x32_bf16 v[82:85], v[236:239], v[188:191], v[82:85]
	v_mfma_f32_16x16x32_bf16 v[70:73], v[228:231], v[196:199], v[70:73]
	v_mfma_f32_16x16x32_bf16 v[66:69], v[236:239], v[196:199], v[66:69]
	v_mfma_f32_16x16x32_bf16 v[118:121], v[232:235], v[176:179], v[118:121]
	v_mfma_f32_16x16x32_bf16 v[114:117], v[240:243], v[176:179], v[114:117]
	v_mfma_f32_16x16x32_bf16 v[102:105], v[232:235], v[184:187], v[102:105]
	v_mfma_f32_16x16x32_bf16 v[98:101], v[240:243], v[184:187], v[98:101]
	v_mfma_f32_16x16x32_bf16 v[86:89], v[232:235], v[192:195], v[86:89]
	v_mfma_f32_16x16x32_bf16 v[82:85], v[240:243], v[192:195], v[82:85]
	v_mfma_f32_16x16x32_bf16 v[70:73], v[232:235], v[224:227], v[70:73]
	v_mfma_f32_16x16x32_bf16 v[66:69], v[240:243], v[224:227], v[66:69]
	s_barrier
	s_mov_b32 m0, s57
	ds_read_b128 v[172:175], v155 offset:49152
	ds_read_b128 v[176:179], v155 offset:50176
	ds_read_b128 v[180:183], v155 offset:51200
	ds_read_b128 v[184:187], v155 offset:52224
	ds_read_b128 v[188:191], v155 offset:53248
	ds_read_b128 v[192:195], v155 offset:54272
	ds_read_b128 v[196:199], v155 offset:55296
	ds_read_b128 v[224:227], v155 offset:56320
	global_load_lds_dwordx4 v134, s[78:79]
	s_mov_b32 m0, s58
	s_nop 0
	global_load_lds_dwordx4 v132, s[78:79]
	s_barrier
	s_waitcnt lgkmcnt(0)
	v_mfma_f32_16x16x32_bf16 v[62:65], v[140:143], v[172:175], v[62:65]
	v_mfma_f32_16x16x32_bf16 v[58:61], v[148:151], v[172:175], v[58:61]
	v_mfma_f32_16x16x32_bf16 v[46:49], v[140:143], v[180:183], v[46:49]
	v_mfma_f32_16x16x32_bf16 v[42:45], v[148:151], v[180:183], v[42:45]
	v_mfma_f32_16x16x32_bf16 v[30:33], v[140:143], v[188:191], v[30:33]
	v_mfma_f32_16x16x32_bf16 v[26:29], v[148:151], v[188:191], v[26:29]
	v_mfma_f32_16x16x32_bf16 v[14:17], v[140:143], v[196:199], v[14:17]
	v_mfma_f32_16x16x32_bf16 v[10:13], v[148:151], v[196:199], v[10:13]
	v_mfma_f32_16x16x32_bf16 v[62:65], v[144:147], v[176:179], v[62:65]
	v_mfma_f32_16x16x32_bf16 v[58:61], v[168:171], v[176:179], v[58:61]
	v_mfma_f32_16x16x32_bf16 v[46:49], v[144:147], v[184:187], v[46:49]
	v_mfma_f32_16x16x32_bf16 v[42:45], v[168:171], v[184:187], v[42:45]
	v_mfma_f32_16x16x32_bf16 v[30:33], v[144:147], v[192:195], v[30:33]
	v_mfma_f32_16x16x32_bf16 v[26:29], v[168:171], v[192:195], v[26:29]
	v_mfma_f32_16x16x32_bf16 v[14:17], v[144:147], v[224:227], v[14:17]
	v_mfma_f32_16x16x32_bf16 v[10:13], v[168:171], v[224:227], v[10:13]
	s_barrier
	s_add_u32 s0, s48, 0x160080
	s_addc_u32 s1, s49, 0
	s_add_i32 s48, s50, s52
	s_mov_b32 m0, s48
	s_nop 0
	global_load_lds_dwordx4 v0, s[0:1]
	s_add_i32 m0, s48, 0x2000
	s_nop 0
	global_load_lds_dwordx4 v130, s[0:1]
	s_waitcnt vmcnt(6)
	s_barrier
	v_mfma_f32_16x16x32_bf16 v[54:57], v[228:231], v[172:175], v[54:57]
	v_mfma_f32_16x16x32_bf16 v[50:53], v[236:239], v[172:175], v[50:53]
	v_mfma_f32_16x16x32_bf16 v[38:41], v[228:231], v[180:183], v[38:41]
	v_mfma_f32_16x16x32_bf16 v[34:37], v[236:239], v[180:183], v[34:37]
	v_mfma_f32_16x16x32_bf16 v[22:25], v[228:231], v[188:191], v[22:25]
	v_mfma_f32_16x16x32_bf16 v[18:21], v[236:239], v[188:191], v[18:21]
	v_mfma_f32_16x16x32_bf16 v[6:9], v[228:231], v[196:199], v[6:9]
	v_mfma_f32_16x16x32_bf16 v[2:5], v[236:239], v[196:199], v[2:5]
	v_mfma_f32_16x16x32_bf16 v[54:57], v[232:235], v[176:179], v[54:57]
	v_mfma_f32_16x16x32_bf16 v[50:53], v[240:243], v[176:179], v[50:53]
	v_mfma_f32_16x16x32_bf16 v[38:41], v[232:235], v[184:187], v[38:41]
	v_mfma_f32_16x16x32_bf16 v[34:37], v[240:243], v[184:187], v[34:37]
	v_mfma_f32_16x16x32_bf16 v[22:25], v[232:235], v[192:195], v[22:25]
	v_mfma_f32_16x16x32_bf16 v[18:21], v[240:243], v[192:195], v[18:21]
	v_mfma_f32_16x16x32_bf16 v[6:9], v[232:235], v[224:227], v[6:9]
	v_mfma_f32_16x16x32_bf16 v[2:5], v[240:243], v[224:227], v[2:5]
	s_barrier
	s_add_u32 s13, s13, 0x100
	s_addc_u32 s68, s68, 0
	s_cmp_ge_i32 s69, s39
	s_mov_b64 s[0:1], s[46:47]
	s_mov_b32 s48, s69
	s_cbranch_scc0 .LBB0_37
	s_cmp_eq_u32 s65, 2
	s_cbranch_scc1 .Lepi10_orig
	v_readlane_b32 s90, v255, 17
	v_readlane_b32 s91, v255, 18
	v_readlane_b32 s96, v255, 19
	v_readlane_b32 s97, v255, 20
	v_lshl_or_b32 v156, s66, 8, v154
	v_lshlrev_b32_e32 v156, 2, v156
	v_lshl_add_u32 v157, v152, 13, v156
	s_lshl_b32 s72, s67, 21
	s_add_u32 s74, s22, s72
	s_addc_u32 s75, s23, 0
	s_add_u32 s76, s22, s72
	s_addc_u32 s77, s23, 0
	s_lshr_b32 s73, s67, 3
	s_mul_i32 s73, s73, 0xc000
	s_add_u32 s73, s73, 0xa000
	s_add_u32 s70, s90, s73
	s_addc_u32 s71, s91, 0
	global_load_dwordx4 v[140:143], v156, s[70:71]
	global_load_dwordx4 v[144:147], v156, s[70:71] offset:64
	global_load_dwordx4 v[148:151], v156, s[70:71] offset:512
	global_load_dwordx4 v[168:171], v156, s[70:71] offset:576
	global_load_dwordx4 v[224:227], v157, s[74:75] nt
	global_load_dwordx4 v[228:231], v157, s[74:75] offset:64 nt
	global_load_dwordx4 v[232:235], v157, s[74:75] offset:512 nt
	global_load_dwordx4 v[236:239], v157, s[74:75] offset:576 nt
	s_add_u32 s74, s74, 0x20000
	s_addc_u32 s75, s75, 0
	global_load_dwordx4 v[240:243], v157, s[74:75] nt
	global_load_dwordx4 v[244:247], v157, s[74:75] offset:64 nt
	s_waitcnt vmcnt(5)
	v_pk_fma_f32 v[128:129], v[128:129], v[142:143], v[226:227]
	v_pk_fma_f32 v[126:127], v[126:127], v[140:141], v[224:225]
	global_store_dwordx4 v157, v[126:129], s[76:77] nt
	global_load_dwordx4 v[224:227], v157, s[74:75] offset:512 nt
	s_waitcnt vmcnt(6)
	v_pk_fma_f32 v[124:125], v[124:125], v[146:147], v[230:231]
	v_pk_fma_f32 v[122:123], v[122:123], v[144:145], v[228:229]
	global_store_dwordx4 v157, v[122:125], s[76:77] offset:64 nt
	global_load_dwordx4 v[228:231], v157, s[74:75] offset:576 nt
	s_waitcnt vmcnt(7)
	v_pk_fma_f32 v[120:121], v[120:121], v[150:151], v[234:235]
	v_pk_fma_f32 v[118:119], v[118:119], v[148:149], v[232:233]
	global_store_dwordx4 v157, v[118:121], s[76:77] offset:512 nt
	s_add_u32 s74, s74, 0x20000
	s_addc_u32 s75, s75, 0
	global_load_dwordx4 v[232:235], v157, s[74:75] nt
	s_waitcnt vmcnt(8)
	v_pk_fma_f32 v[116:117], v[116:117], v[170:171], v[238:239]
	v_pk_fma_f32 v[114:115], v[114:115], v[168:169], v[236:237]
	global_store_dwordx4 v157, v[114:117], s[76:77] offset:576 nt
	global_load_dwordx4 v[236:239], v157, s[74:75] offset:64 nt
	s_add_u32 s76, s76, 0x20000
	s_addc_u32 s77, s77, 0
	s_waitcnt vmcnt(9)
	v_pk_fma_f32 v[112:113], v[112:113], v[142:143], v[242:243]
	v_pk_fma_f32 v[110:111], v[110:111], v[140:141], v[240:241]
	global_store_dwordx4 v157, v[110:113], s[76:77] nt
	global_load_dwordx4 v[240:243], v157, s[74:75] offset:512 nt
	s_waitcnt vmcnt(10)
	v_pk_fma_f32 v[108:109], v[108:109], v[146:147], v[246:247]
	v_pk_fma_f32 v[106:107], v[106:107], v[144:145], v[244:245]
	global_store_dwordx4 v157, v[106:109], s[76:77] offset:64 nt
	global_load_dwordx4 v[244:247], v157, s[74:75] offset:576 nt
	s_waitcnt vmcnt(10)
	v_pk_fma_f32 v[104:105], v[104:105], v[150:151], v[226:227]
	v_pk_fma_f32 v[102:103], v[102:103], v[148:149], v[224:225]
	global_store_dwordx4 v157, v[102:105], s[76:77] offset:512 nt
	s_add_u32 s74, s74, 0x20000
	s_addc_u32 s75, s75, 0
	global_load_dwordx4 v[224:227], v157, s[74:75] nt
	s_waitcnt vmcnt(10)
	v_pk_fma_f32 v[100:101], v[100:101], v[170:171], v[230:231]
	v_pk_fma_f32 v[98:99], v[98:99], v[168:169], v[228:229]
	global_store_dwordx4 v157, v[98:101], s[76:77] offset:576 nt
	global_load_dwordx4 v[228:231], v157, s[74:75] offset:64 nt
	s_add_u32 s76, s76, 0x20000
	s_addc_u32 s77, s77, 0
	s_waitcnt vmcnt(10)
	v_pk_fma_f32 v[96:97], v[96:97], v[142:143], v[234:235]
	v_pk_fma_f32 v[94:95], v[94:95], v[140:141], v[232:233]
	global_store_dwordx4 v157, v[94:97], s[76:77] nt
	global_load_dwordx4 v[232:235], v157, s[74:75] offset:512 nt
	s_waitcnt vmcnt(10)
	v_pk_fma_f32 v[92:93], v[92:93], v[146:147], v[238:239]
	v_pk_fma_f32 v[90:91], v[90:91], v[144:145], v[236:237]
	global_store_dwordx4 v157, v[90:93], s[76:77] offset:64 nt
	global_load_dwordx4 v[236:239], v157, s[74:75] offset:576 nt
	s_waitcnt vmcnt(10)
	v_pk_fma_f32 v[88:89], v[88:89], v[150:151], v[242:243]
	v_pk_fma_f32 v[86:87], v[86:87], v[148:149], v[240:241]
	global_store_dwordx4 v157, v[86:89], s[76:77] offset:512 nt
	s_add_u32 s74, s74, 0xa0000
	s_addc_u32 s75, s75, 0
	global_load_dwordx4 v[240:243], v157, s[74:75] nt
	s_waitcnt vmcnt(10)
	v_pk_fma_f32 v[84:85], v[84:85], v[170:171], v[246:247]
	v_pk_fma_f32 v[82:83], v[82:83], v[168:169], v[244:245]
	global_store_dwordx4 v157, v[82:85], s[76:77] offset:576 nt
	global_load_dwordx4 v[244:247], v157, s[74:75] offset:64 nt
	s_add_u32 s76, s76, 0x20000
	s_addc_u32 s77, s77, 0
	s_waitcnt vmcnt(10)
	v_pk_fma_f32 v[80:81], v[80:81], v[142:143], v[226:227]
	v_pk_fma_f32 v[78:79], v[78:79], v[140:141], v[224:225]
	global_store_dwordx4 v157, v[78:81], s[76:77] nt
	global_load_dwordx4 v[224:227], v157, s[74:75] offset:512 nt
	s_waitcnt vmcnt(10)
	v_pk_fma_f32 v[76:77], v[76:77], v[146:147], v[230:231]
	v_pk_fma_f32 v[74:75], v[74:75], v[144:145], v[228:229]
	global_store_dwordx4 v157, v[74:77], s[76:77] offset:64 nt
	global_load_dwordx4 v[228:231], v157, s[74:75] offset:576 nt
	s_waitcnt vmcnt(10)
	v_pk_fma_f32 v[72:73], v[72:73], v[150:151], v[234:235]
	v_pk_fma_f32 v[70:71], v[70:71], v[148:149], v[232:233]
	global_store_dwordx4 v157, v[70:73], s[76:77] offset:512 nt
	s_add_u32 s74, s74, 0x20000
	s_addc_u32 s75, s75, 0
	global_load_dwordx4 v[232:235], v157, s[74:75] nt
	s_waitcnt vmcnt(10)
	v_pk_fma_f32 v[68:69], v[68:69], v[170:171], v[238:239]
	v_pk_fma_f32 v[66:67], v[66:67], v[168:169], v[236:237]
	global_store_dwordx4 v157, v[66:69], s[76:77] offset:576 nt
	global_load_dwordx4 v[236:239], v157, s[74:75] offset:64 nt
	s_add_u32 s76, s76, 0xa0000
	s_addc_u32 s77, s77, 0
	s_waitcnt vmcnt(10)
	v_pk_fma_f32 v[64:65], v[64:65], v[142:143], v[242:243]
	v_pk_fma_f32 v[62:63], v[62:63], v[140:141], v[240:241]
	global_store_dwordx4 v157, v[62:65], s[76:77] nt
	global_load_dwordx4 v[240:243], v157, s[74:75] offset:512 nt
	s_waitcnt vmcnt(10)
	v_pk_fma_f32 v[60:61], v[60:61], v[146:147], v[246:247]
	v_pk_fma_f32 v[58:59], v[58:59], v[144:145], v[244:245]
	global_store_dwordx4 v157, v[58:61], s[76:77] offset:64 nt
	global_load_dwordx4 v[244:247], v157, s[74:75] offset:576 nt
	s_waitcnt vmcnt(10)
	v_pk_fma_f32 v[56:57], v[56:57], v[150:151], v[226:227]
	v_pk_fma_f32 v[54:55], v[54:55], v[148:149], v[224:225]
	global_store_dwordx4 v157, v[54:57], s[76:77] offset:512 nt
	s_add_u32 s74, s74, 0x20000
	s_addc_u32 s75, s75, 0
	global_load_dwordx4 v[224:227], v157, s[74:75] nt
	s_waitcnt vmcnt(10)
	v_pk_fma_f32 v[52:53], v[52:53], v[170:171], v[230:231]
	v_pk_fma_f32 v[50:51], v[50:51], v[168:169], v[228:229]
	global_store_dwordx4 v157, v[50:53], s[76:77] offset:576 nt
	global_load_dwordx4 v[228:231], v157, s[74:75] offset:64 nt
	s_add_u32 s76, s76, 0x20000
	s_addc_u32 s77, s77, 0
	s_waitcnt vmcnt(10)
	v_pk_fma_f32 v[48:49], v[48:49], v[142:143], v[234:235]
	v_pk_fma_f32 v[46:47], v[46:47], v[140:141], v[232:233]
	global_store_dwordx4 v157, v[46:49], s[76:77] nt
	global_load_dwordx4 v[232:235], v157, s[74:75] offset:512 nt
	s_waitcnt vmcnt(10)
	v_pk_fma_f32 v[44:45], v[44:45], v[146:147], v[238:239]
	v_pk_fma_f32 v[42:43], v[42:43], v[144:145], v[236:237]
	global_store_dwordx4 v157, v[42:45], s[76:77] offset:64 nt
	global_load_dwordx4 v[236:239], v157, s[74:75] offset:576 nt
	s_waitcnt vmcnt(10)
	v_pk_fma_f32 v[40:41], v[40:41], v[150:151], v[242:243]
	v_pk_fma_f32 v[38:39], v[38:39], v[148:149], v[240:241]
	global_store_dwordx4 v157, v[38:41], s[76:77] offset:512 nt
	s_add_u32 s74, s74, 0x20000
	s_addc_u32 s75, s75, 0
	global_load_dwordx4 v[240:243], v157, s[74:75] nt
	s_waitcnt vmcnt(10)
	v_pk_fma_f32 v[36:37], v[36:37], v[170:171], v[246:247]
	v_pk_fma_f32 v[34:35], v[34:35], v[168:169], v[244:245]
	global_store_dwordx4 v157, v[34:37], s[76:77] offset:576 nt
	global_load_dwordx4 v[244:247], v157, s[74:75] offset:64 nt
	s_add_u32 s76, s76, 0x20000
	s_addc_u32 s77, s77, 0
	s_waitcnt vmcnt(10)
	v_pk_fma_f32 v[32:33], v[32:33], v[142:143], v[226:227]
	v_pk_fma_f32 v[30:31], v[30:31], v[140:141], v[224:225]
	global_store_dwordx4 v157, v[30:33], s[76:77] nt
	global_load_dwordx4 v[224:227], v157, s[74:75] offset:512 nt
	s_waitcnt vmcnt(10)
	v_pk_fma_f32 v[28:29], v[28:29], v[146:147], v[230:231]
	v_pk_fma_f32 v[26:27], v[26:27], v[144:145], v[228:229]
	global_store_dwordx4 v157, v[26:29], s[76:77] offset:64 nt
	global_load_dwordx4 v[228:231], v157, s[74:75] offset:576 nt
	s_waitcnt vmcnt(10)
	v_pk_fma_f32 v[24:25], v[24:25], v[150:151], v[234:235]
	v_pk_fma_f32 v[22:23], v[22:23], v[148:149], v[232:233]
	global_store_dwordx4 v157, v[22:25], s[76:77] offset:512 nt
	s_waitcnt vmcnt(9)
	v_pk_fma_f32 v[20:21], v[20:21], v[170:171], v[238:239]
	v_pk_fma_f32 v[18:19], v[18:19], v[168:169], v[236:237]
	global_store_dwordx4 v157, v[18:21], s[76:77] offset:576 nt
	s_add_u32 s76, s76, 0x20000
	s_addc_u32 s77, s77, 0
	s_waitcnt vmcnt(8)
	v_pk_fma_f32 v[16:17], v[16:17], v[142:143], v[242:243]
	v_pk_fma_f32 v[14:15], v[14:15], v[140:141], v[240:241]
	global_store_dwordx4 v157, v[14:17], s[76:77] nt
	s_waitcnt vmcnt(7)
	v_pk_fma_f32 v[12:13], v[12:13], v[146:147], v[246:247]
	v_pk_fma_f32 v[10:11], v[10:11], v[144:145], v[244:245]
	global_store_dwordx4 v157, v[10:13], s[76:77] offset:64 nt
	s_waitcnt vmcnt(6)
	v_pk_fma_f32 v[8:9], v[8:9], v[150:151], v[226:227]
	v_pk_fma_f32 v[6:7], v[6:7], v[148:149], v[224:225]
	global_store_dwordx4 v157, v[6:9], s[76:77] offset:512 nt
	s_waitcnt vmcnt(5)
	v_pk_fma_f32 v[4:5], v[4:5], v[170:171], v[230:231]
	v_pk_fma_f32 v[2:3], v[2:3], v[168:169], v[228:229]
	global_store_dwordx4 v157, v[2:5], s[76:77] offset:576 nt
	s_branch .LBB0_24

.LBB0_234:
	s_add_u32 s39, s46, 0xfff80080
	s_addc_u32 s48, s47, -1
	s_add_i32 s62, 0, 0x10000
	v_add_u32_e32 v156, s62, v141
	ds_read_b128 v[144:147], v156
	ds_read_b128 v[148:151], v156 offset:1024
	ds_read_b128 v[152:155], v156 offset:2048
	ds_read_b128 v[168:171], v156 offset:3072
	s_cmp_eq_u32 s13, 28
	s_cselect_b32 s51, s43, s48
	s_cselect_b32 s50, s42, s39
	s_cselect_b32 s49, s45, s12
	s_cselect_b32 s48, s44, s1
	s_add_i32 m0, s53, 0xc000
	ds_read_b128 v[172:175], v143
	ds_read_b128 v[176:179], v143 offset:1024
	ds_read_b128 v[180:183], v143 offset:2048
	ds_read_b128 v[184:187], v143 offset:3072
	ds_read_b128 v[188:191], v143 offset:4096
	ds_read_b128 v[192:195], v143 offset:5120
	ds_read_b128 v[196:199], v143 offset:6144
	ds_read_b128 v[224:227], v143 offset:7168
	global_load_lds_dwordx4 v136, s[46:47]
	s_add_i32 m0, s53, 0xe000
	s_nop 0
	global_load_lds_dwordx4 v138, s[46:47]
	s_waitcnt lgkmcnt(8)
	s_barrier
	s_waitcnt lgkmcnt(0)
	v_mfma_f32_16x16x32_bf16 v[126:129], v[144:147], v[172:175], v[126:129]
	v_mfma_f32_16x16x32_bf16 v[122:125], v[152:155], v[172:175], v[122:125]
	v_mfma_f32_16x16x32_bf16 v[118:121], v[144:147], v[180:183], v[118:121]
	v_mfma_f32_16x16x32_bf16 v[114:117], v[152:155], v[180:183], v[114:117]
	v_mfma_f32_16x16x32_bf16 v[102:105], v[144:147], v[188:191], v[102:105]
	v_mfma_f32_16x16x32_bf16 v[98:101], v[152:155], v[188:191], v[98:101]
	v_mfma_f32_16x16x32_bf16 v[86:89], v[144:147], v[196:199], v[86:89]
	v_mfma_f32_16x16x32_bf16 v[82:85], v[152:155], v[196:199], v[82:85]
	v_mfma_f32_16x16x32_bf16 v[126:129], v[148:151], v[176:179], v[126:129]
	v_mfma_f32_16x16x32_bf16 v[122:125], v[168:171], v[176:179], v[122:125]
	v_mfma_f32_16x16x32_bf16 v[118:121], v[148:151], v[184:187], v[118:121]
	v_mfma_f32_16x16x32_bf16 v[114:117], v[168:171], v[184:187], v[114:117]
	v_mfma_f32_16x16x32_bf16 v[102:105], v[148:151], v[192:195], v[102:105]
	v_mfma_f32_16x16x32_bf16 v[98:101], v[168:171], v[192:195], v[98:101]
	v_mfma_f32_16x16x32_bf16 v[86:89], v[148:151], v[224:227], v[86:89]
	v_mfma_f32_16x16x32_bf16 v[82:85], v[168:171], v[224:227], v[82:85]
	s_barrier
	s_add_i32 s39, 0, 0x14000
	v_add_u32_e32 v156, s39, v141
	s_add_i32 s62, s62, s52
	ds_read_b128 v[228:231], v156
	ds_read_b128 v[232:235], v156 offset:1024
	ds_read_b128 v[236:239], v156 offset:2048
	ds_read_b128 v[240:243], v156 offset:3072
	s_add_u32 s76, s48, s94
	s_addc_u32 s77, s49, s95
	s_mov_b32 m0, s62
	s_nop 0
	global_load_lds_dwordx4 v0, s[48:49]
	s_add_i32 m0, s62, 0x2000
	s_nop 0
	global_load_lds_dwordx4 v130, s[48:49]
	s_barrier
	s_waitcnt lgkmcnt(0)
	v_mfma_f32_16x16x32_bf16 v[110:113], v[228:231], v[172:175], v[110:113]
	v_mfma_f32_16x16x32_bf16 v[106:109], v[236:239], v[172:175], v[106:109]
	v_mfma_f32_16x16x32_bf16 v[94:97], v[228:231], v[180:183], v[94:97]
	v_mfma_f32_16x16x32_bf16 v[90:93], v[236:239], v[180:183], v[90:93]
	v_mfma_f32_16x16x32_bf16 v[78:81], v[228:231], v[188:191], v[78:81]
	v_mfma_f32_16x16x32_bf16 v[74:77], v[236:239], v[188:191], v[74:77]
	v_mfma_f32_16x16x32_bf16 v[70:73], v[228:231], v[196:199], v[70:73]
	v_mfma_f32_16x16x32_bf16 v[66:69], v[236:239], v[196:199], v[66:69]
	v_mfma_f32_16x16x32_bf16 v[110:113], v[232:235], v[176:179], v[110:113]
	v_mfma_f32_16x16x32_bf16 v[106:109], v[240:243], v[176:179], v[106:109]
	v_mfma_f32_16x16x32_bf16 v[94:97], v[232:235], v[184:187], v[94:97]
	v_mfma_f32_16x16x32_bf16 v[90:93], v[240:243], v[184:187], v[90:93]
	v_mfma_f32_16x16x32_bf16 v[78:81], v[232:235], v[192:195], v[78:81]
	v_mfma_f32_16x16x32_bf16 v[74:77], v[240:243], v[192:195], v[74:77]
	v_mfma_f32_16x16x32_bf16 v[70:73], v[232:235], v[224:227], v[70:73]
	v_mfma_f32_16x16x32_bf16 v[66:69], v[240:243], v[224:227], v[66:69]
	s_barrier
	s_mov_b32 m0, s53
	s_add_u32 s78, s50, s94
	s_addc_u32 s79, s51, s95
	ds_read_b128 v[172:175], v143 offset:16384
	ds_read_b128 v[176:179], v143 offset:17408
	ds_read_b128 v[180:183], v143 offset:18432
	ds_read_b128 v[184:187], v143 offset:19456
	ds_read_b128 v[188:191], v143 offset:20480
	ds_read_b128 v[192:195], v143 offset:21504
	ds_read_b128 v[196:199], v143 offset:22528
	ds_read_b128 v[224:227], v143 offset:23552
	global_load_lds_dwordx4 v134, s[50:51]
	s_mov_b32 m0, s54
	s_nop 0
	global_load_lds_dwordx4 v132, s[50:51]
	s_barrier
	s_waitcnt lgkmcnt(0)
	v_mfma_f32_16x16x32_bf16 v[62:65], v[144:147], v[172:175], v[62:65]
	v_mfma_f32_16x16x32_bf16 v[58:61], v[152:155], v[172:175], v[58:61]
	v_mfma_f32_16x16x32_bf16 v[54:57], v[144:147], v[180:183], v[54:57]
	v_mfma_f32_16x16x32_bf16 v[50:53], v[152:155], v[180:183], v[50:53]
	v_mfma_f32_16x16x32_bf16 v[38:41], v[144:147], v[188:191], v[38:41]
	v_mfma_f32_16x16x32_bf16 v[34:37], v[152:155], v[188:191], v[34:37]
	v_mfma_f32_16x16x32_bf16 v[22:25], v[144:147], v[196:199], v[22:25]
	v_mfma_f32_16x16x32_bf16 v[18:21], v[152:155], v[196:199], v[18:21]
	v_mfma_f32_16x16x32_bf16 v[62:65], v[148:151], v[176:179], v[62:65]
	v_mfma_f32_16x16x32_bf16 v[58:61], v[168:171], v[176:179], v[58:61]
	v_mfma_f32_16x16x32_bf16 v[54:57], v[148:151], v[184:187], v[54:57]
	v_mfma_f32_16x16x32_bf16 v[50:53], v[168:171], v[184:187], v[50:53]
	v_mfma_f32_16x16x32_bf16 v[38:41], v[148:151], v[192:195], v[38:41]
	v_mfma_f32_16x16x32_bf16 v[34:37], v[168:171], v[192:195], v[34:37]
	v_mfma_f32_16x16x32_bf16 v[22:25], v[148:151], v[224:227], v[22:25]
	v_mfma_f32_16x16x32_bf16 v[18:21], v[168:171], v[224:227], v[18:21]
	s_barrier
	s_add_u32 s62, s48, 0x80000
	s_addc_u32 s63, s49, 0
	s_add_i32 s39, s39, s52
	s_mov_b32 m0, s39
	s_nop 0
	global_load_lds_dwordx4 v0, s[62:63]
	s_add_i32 m0, s39, 0x2000
	s_nop 0
	global_load_lds_dwordx4 v130, s[62:63]
	s_waitcnt vmcnt(6)
	s_barrier
	v_mfma_f32_16x16x32_bf16 v[46:49], v[228:231], v[172:175], v[46:49]
	v_mfma_f32_16x16x32_bf16 v[42:45], v[236:239], v[172:175], v[42:45]
	v_mfma_f32_16x16x32_bf16 v[30:33], v[228:231], v[180:183], v[30:33]
	v_mfma_f32_16x16x32_bf16 v[26:29], v[236:239], v[180:183], v[26:29]
	v_mfma_f32_16x16x32_bf16 v[14:17], v[228:231], v[188:191], v[14:17]
	v_mfma_f32_16x16x32_bf16 v[10:13], v[236:239], v[188:191], v[10:13]
	v_mfma_f32_16x16x32_bf16 v[6:9], v[228:231], v[196:199], v[6:9]
	v_mfma_f32_16x16x32_bf16 v[2:5], v[236:239], v[196:199], v[2:5]
	v_mfma_f32_16x16x32_bf16 v[46:49], v[232:235], v[176:179], v[46:49]
	v_mfma_f32_16x16x32_bf16 v[42:45], v[240:243], v[176:179], v[42:45]
	v_mfma_f32_16x16x32_bf16 v[30:33], v[232:235], v[184:187], v[30:33]
	v_mfma_f32_16x16x32_bf16 v[26:29], v[240:243], v[184:187], v[26:29]
	v_mfma_f32_16x16x32_bf16 v[14:17], v[232:235], v[192:195], v[14:17]
	v_mfma_f32_16x16x32_bf16 v[10:13], v[240:243], v[192:195], v[10:13]
	v_mfma_f32_16x16x32_bf16 v[6:9], v[232:235], v[224:227], v[6:9]
	v_mfma_f32_16x16x32_bf16 v[2:5], v[240:243], v[224:227], v[2:5]
	s_barrier
	s_add_i32 s39, 0, 0x18000
	v_add_u32_e32 v161, s39, v141
	ds_read_b128 v[144:147], v161
	ds_read_b128 v[148:151], v161 offset:1024
	ds_read_b128 v[152:155], v161 offset:2048
	ds_read_b128 v[168:171], v161 offset:3072
	s_add_u32 s50, s50, 0x80000
	s_addc_u32 s51, s51, 0
	s_mov_b32 m0, s55
	ds_read_b128 v[172:175], v143 offset:32768
	ds_read_b128 v[176:179], v143 offset:33792
	ds_read_b128 v[180:183], v143 offset:34816
	ds_read_b128 v[184:187], v143 offset:35840
	ds_read_b128 v[188:191], v143 offset:36864
	ds_read_b128 v[192:195], v143 offset:37888
	ds_read_b128 v[196:199], v143 offset:38912
	ds_read_b128 v[224:227], v143 offset:39936
	global_load_lds_dwordx4 v134, s[50:51]
	s_mov_b32 m0, s56
	s_nop 0
	global_load_lds_dwordx4 v132, s[50:51]
	s_waitcnt lgkmcnt(8)
	s_barrier
	s_waitcnt lgkmcnt(0)
	v_mfma_f32_16x16x32_bf16 v[126:129], v[144:147], v[172:175], v[126:129]
	v_mfma_f32_16x16x32_bf16 v[122:125], v[152:155], v[172:175], v[122:125]
	v_mfma_f32_16x16x32_bf16 v[118:121], v[144:147], v[180:183], v[118:121]
	v_mfma_f32_16x16x32_bf16 v[114:117], v[152:155], v[180:183], v[114:117]
	v_mfma_f32_16x16x32_bf16 v[102:105], v[144:147], v[188:191], v[102:105]
	v_mfma_f32_16x16x32_bf16 v[98:101], v[152:155], v[188:191], v[98:101]
	v_mfma_f32_16x16x32_bf16 v[86:89], v[144:147], v[196:199], v[86:89]
	v_mfma_f32_16x16x32_bf16 v[82:85], v[152:155], v[196:199], v[82:85]
	v_mfma_f32_16x16x32_bf16 v[126:129], v[148:151], v[176:179], v[126:129]
	v_mfma_f32_16x16x32_bf16 v[122:125], v[168:171], v[176:179], v[122:125]
	v_mfma_f32_16x16x32_bf16 v[118:121], v[148:151], v[184:187], v[118:121]
	v_mfma_f32_16x16x32_bf16 v[114:117], v[168:171], v[184:187], v[114:117]
	v_mfma_f32_16x16x32_bf16 v[102:105], v[148:151], v[192:195], v[102:105]
	v_mfma_f32_16x16x32_bf16 v[98:101], v[168:171], v[192:195], v[98:101]
	v_mfma_f32_16x16x32_bf16 v[86:89], v[148:151], v[224:227], v[86:89]
	v_mfma_f32_16x16x32_bf16 v[82:85], v[168:171], v[224:227], v[82:85]
	s_barrier
	s_add_i32 s50, 0, 0x1c000
	s_add_i32 s39, s39, s52
	v_add_u32_e32 v161, s50, v141
	s_mov_b32 m0, s39
	ds_read_b128 v[228:231], v161
	ds_read_b128 v[232:235], v161 offset:1024
	ds_read_b128 v[236:239], v161 offset:2048
	ds_read_b128 v[240:243], v161 offset:3072
	global_load_lds_dwordx4 v0, s[76:77]
	s_add_i32 m0, s39, 0x2000
	s_nop 0
	global_load_lds_dwordx4 v130, s[76:77]
	s_barrier
	s_waitcnt lgkmcnt(0)
	v_mfma_f32_16x16x32_bf16 v[110:113], v[228:231], v[172:175], v[110:113]
	v_mfma_f32_16x16x32_bf16 v[106:109], v[236:239], v[172:175], v[106:109]
	v_mfma_f32_16x16x32_bf16 v[94:97], v[228:231], v[180:183], v[94:97]
	v_mfma_f32_16x16x32_bf16 v[90:93], v[236:239], v[180:183], v[90:93]
	v_mfma_f32_16x16x32_bf16 v[78:81], v[228:231], v[188:191], v[78:81]
	v_mfma_f32_16x16x32_bf16 v[74:77], v[236:239], v[188:191], v[74:77]
	v_mfma_f32_16x16x32_bf16 v[70:73], v[228:231], v[196:199], v[70:73]
	v_mfma_f32_16x16x32_bf16 v[66:69], v[236:239], v[196:199], v[66:69]
	v_mfma_f32_16x16x32_bf16 v[110:113], v[232:235], v[176:179], v[110:113]
	v_mfma_f32_16x16x32_bf16 v[106:109], v[240:243], v[176:179], v[106:109]
	v_mfma_f32_16x16x32_bf16 v[94:97], v[232:235], v[184:187], v[94:97]
	v_mfma_f32_16x16x32_bf16 v[90:93], v[240:243], v[184:187], v[90:93]
	v_mfma_f32_16x16x32_bf16 v[78:81], v[232:235], v[192:195], v[78:81]
	v_mfma_f32_16x16x32_bf16 v[74:77], v[240:243], v[192:195], v[74:77]
	v_mfma_f32_16x16x32_bf16 v[70:73], v[232:235], v[224:227], v[70:73]
	v_mfma_f32_16x16x32_bf16 v[66:69], v[240:243], v[224:227], v[66:69]
	s_barrier
	s_mov_b32 m0, s57
	ds_read_b128 v[172:175], v143 offset:49152
	ds_read_b128 v[176:179], v143 offset:50176
	ds_read_b128 v[180:183], v143 offset:51200
	ds_read_b128 v[184:187], v143 offset:52224
	ds_read_b128 v[188:191], v143 offset:53248
	ds_read_b128 v[192:195], v143 offset:54272
	ds_read_b128 v[196:199], v143 offset:55296
	ds_read_b128 v[224:227], v143 offset:56320
	global_load_lds_dwordx4 v134, s[78:79]
	s_mov_b32 m0, s58
	s_nop 0
	global_load_lds_dwordx4 v132, s[78:79]
	s_barrier
	s_waitcnt lgkmcnt(0)
	v_mfma_f32_16x16x32_bf16 v[62:65], v[144:147], v[172:175], v[62:65]
	v_mfma_f32_16x16x32_bf16 v[58:61], v[152:155], v[172:175], v[58:61]
	v_mfma_f32_16x16x32_bf16 v[54:57], v[144:147], v[180:183], v[54:57]
	v_mfma_f32_16x16x32_bf16 v[50:53], v[152:155], v[180:183], v[50:53]
	v_mfma_f32_16x16x32_bf16 v[38:41], v[144:147], v[188:191], v[38:41]
	v_mfma_f32_16x16x32_bf16 v[34:37], v[152:155], v[188:191], v[34:37]
	v_mfma_f32_16x16x32_bf16 v[22:25], v[144:147], v[196:199], v[22:25]
	v_mfma_f32_16x16x32_bf16 v[18:21], v[152:155], v[196:199], v[18:21]
	v_mfma_f32_16x16x32_bf16 v[62:65], v[148:151], v[176:179], v[62:65]
	v_mfma_f32_16x16x32_bf16 v[58:61], v[168:171], v[176:179], v[58:61]
	v_mfma_f32_16x16x32_bf16 v[54:57], v[148:151], v[184:187], v[54:57]
	v_mfma_f32_16x16x32_bf16 v[50:53], v[168:171], v[184:187], v[50:53]
	v_mfma_f32_16x16x32_bf16 v[38:41], v[148:151], v[192:195], v[38:41]
	v_mfma_f32_16x16x32_bf16 v[34:37], v[168:171], v[192:195], v[34:37]
	v_mfma_f32_16x16x32_bf16 v[22:25], v[148:151], v[224:227], v[22:25]
	v_mfma_f32_16x16x32_bf16 v[18:21], v[168:171], v[224:227], v[18:21]
	s_barrier
	s_add_u32 s48, s48, 0x80080
	s_addc_u32 s49, s49, 0
	s_add_i32 s39, s50, s52
	s_mov_b32 m0, s39
	s_nop 0
	global_load_lds_dwordx4 v0, s[48:49]
	s_add_i32 m0, s39, 0x2000
	s_nop 0
	global_load_lds_dwordx4 v130, s[48:49]
	s_waitcnt vmcnt(6)
	s_barrier
	v_mfma_f32_16x16x32_bf16 v[46:49], v[228:231], v[172:175], v[46:49]
	v_mfma_f32_16x16x32_bf16 v[42:45], v[236:239], v[172:175], v[42:45]
	v_mfma_f32_16x16x32_bf16 v[30:33], v[228:231], v[180:183], v[30:33]
	v_mfma_f32_16x16x32_bf16 v[26:29], v[236:239], v[180:183], v[26:29]
	v_mfma_f32_16x16x32_bf16 v[14:17], v[228:231], v[188:191], v[14:17]
	v_mfma_f32_16x16x32_bf16 v[10:13], v[236:239], v[188:191], v[10:13]
	v_mfma_f32_16x16x32_bf16 v[6:9], v[228:231], v[196:199], v[6:9]
	v_mfma_f32_16x16x32_bf16 v[2:5], v[236:239], v[196:199], v[2:5]
	v_mfma_f32_16x16x32_bf16 v[46:49], v[232:235], v[176:179], v[46:49]
	v_mfma_f32_16x16x32_bf16 v[42:45], v[240:243], v[176:179], v[42:45]
	v_mfma_f32_16x16x32_bf16 v[30:33], v[232:235], v[184:187], v[30:33]
	v_mfma_f32_16x16x32_bf16 v[26:29], v[240:243], v[184:187], v[26:29]
	v_mfma_f32_16x16x32_bf16 v[14:17], v[232:235], v[192:195], v[14:17]
	v_mfma_f32_16x16x32_bf16 v[10:13], v[240:243], v[192:195], v[10:13]
	v_mfma_f32_16x16x32_bf16 v[6:9], v[232:235], v[224:227], v[6:9]
	v_mfma_f32_16x16x32_bf16 v[2:5], v[240:243], v[224:227], v[2:5]
	s_barrier
	s_add_i32 s13, s13, 2
	s_add_u32 s46, s46, 0x100
	s_addc_u32 s47, s47, 0
	s_add_u32 s1, s1, 0x100
	s_addc_u32 s12, s12, 0
	s_cmp_gt_u32 s13, 29
	s_cbranch_scc0 .LBB0_234
	v_readlane_b32 s6, v255, 23
	v_lshl_add_u32 v150, s61, 8, v140
	v_lshl_or_b32 v144, s60, 8, v142
	v_readlane_b32 s7, v255, 24
	v_ashrrev_i32_e32 v145, 31, v144
	s_movk_i32 s1, 0x5800
	v_mov_b64_e32 v[146:147], s[6:7]
	v_cvt_pk_bf16_f32 v70, v70, v71
	v_cvt_pk_bf16_f32 v71, v72, v73
	v_cvt_pk_bf16_f32 v72, v66, v67
	v_add_u32_e32 v66, 0x80, v150
	v_mad_i64_i32 v[148:149], s[12:13], v150, s1, v[146:147]
	v_lshlrev_b64 v[144:145], 1, v[144:145]
	v_cvt_pk_bf16_f32 v110, v110, v111
	v_cvt_pk_bf16_f32 v111, v112, v113
	v_cvt_pk_bf16_f32 v112, v106, v107
	v_or_b32_e32 v106, 16, v150
	v_mad_i64_i32 v[66:67], s[12:13], v66, s1, v[146:147]
	v_cvt_pk_bf16_f32 v46, v46, v47
	v_cvt_pk_bf16_f32 v47, v48, v49
	v_cvt_pk_bf16_f32 v48, v42, v43
	v_add_u32_e32 v42, 0x90, v150
	v_lshl_add_u64 v[148:149], v[148:149], 0, v[144:145]
	v_cvt_pk_bf16_f32 v113, v108, v109
	v_mad_i64_i32 v[106:107], s[12:13], v106, s1, v[146:147]
	v_cvt_pk_bf16_f32 v94, v94, v95
	v_cvt_pk_bf16_f32 v95, v96, v97
	v_cvt_pk_bf16_f32 v96, v90, v91
	v_or_b32_e32 v90, 32, v150
	v_lshl_add_u64 v[66:67], v[66:67], 0, v[144:145]
	v_cvt_pk_bf16_f32 v49, v44, v45
	v_mad_i64_i32 v[42:43], s[12:13], v42, s1, v[146:147]
	v_cvt_pk_bf16_f32 v30, v30, v31
	v_cvt_pk_bf16_f32 v31, v32, v33
	v_cvt_pk_bf16_f32 v32, v26, v27
	v_add_u32_e32 v26, 0xa0, v150
	global_store_dwordx4 v[148:149], v[110:113], off offset:256
	v_cvt_pk_bf16_f32 v97, v92, v93
	v_mad_i64_i32 v[90:91], s[12:13], v90, s1, v[146:147]
	v_lshl_add_u64 v[110:111], v[106:107], 0, v[144:145]
	v_cvt_pk_bf16_f32 v78, v78, v79
	v_cvt_pk_bf16_f32 v79, v80, v81
	v_cvt_pk_bf16_f32 v80, v74, v75
	v_or_b32_e32 v74, 48, v150
	global_store_dwordx4 v[66:67], v[46:49], off offset:256
	v_cvt_pk_bf16_f32 v33, v28, v29
	v_mad_i64_i32 v[26:27], s[12:13], v26, s1, v[146:147]
	v_lshl_add_u64 v[46:47], v[42:43], 0, v[144:145]
	v_cvt_pk_bf16_f32 v14, v14, v15
	v_cvt_pk_bf16_f32 v15, v16, v17
	v_cvt_pk_bf16_f32 v16, v10, v11
	v_add_u32_e32 v10, 0xb0, v150
	global_store_dwordx4 v[110:111], v[94:97], off offset:256
	v_cvt_pk_bf16_f32 v81, v76, v77
	v_mad_i64_i32 v[74:75], s[12:13], v74, s1, v[146:147]
	v_lshl_add_u64 v[94:95], v[90:91], 0, v[144:145]
	global_store_dwordx4 v[46:47], v[30:33], off offset:256
	v_cvt_pk_bf16_f32 v17, v12, v13
	v_mad_i64_i32 v[10:11], s[12:13], v10, s1, v[146:147]
	v_lshl_add_u64 v[30:31], v[26:27], 0, v[144:145]
	v_cvt_pk_bf16_f32 v126, v126, v127
	v_cvt_pk_bf16_f32 v127, v128, v129
	v_cvt_pk_bf16_f32 v128, v122, v123
	v_cvt_pk_bf16_f32 v129, v124, v125
	v_cvt_pk_bf16_f32 v106, v118, v119
	v_cvt_pk_bf16_f32 v107, v120, v121
	v_cvt_pk_bf16_f32 v108, v114, v115
	v_cvt_pk_bf16_f32 v109, v116, v117
	v_cvt_pk_bf16_f32 v90, v102, v103
	v_cvt_pk_bf16_f32 v91, v104, v105
	v_cvt_pk_bf16_f32 v92, v98, v99
	v_cvt_pk_bf16_f32 v93, v100, v101
	global_store_dwordx4 v[94:95], v[78:81], off offset:256
	v_cvt_pk_bf16_f32 v76, v82, v83
	v_cvt_pk_bf16_f32 v77, v84, v85
	v_lshl_add_u64 v[78:79], v[74:75], 0, v[144:145]
	v_cvt_pk_bf16_f32 v74, v86, v87
	v_cvt_pk_bf16_f32 v75, v88, v89
	v_cvt_pk_bf16_f32 v73, v68, v69
	v_cvt_pk_bf16_f32 v62, v62, v63
	v_cvt_pk_bf16_f32 v63, v64, v65
	v_cvt_pk_bf16_f32 v64, v58, v59
	v_cvt_pk_bf16_f32 v65, v60, v61
	v_cvt_pk_bf16_f32 v42, v54, v55
	v_cvt_pk_bf16_f32 v43, v56, v57
	v_cvt_pk_bf16_f32 v44, v50, v51
	v_cvt_pk_bf16_f32 v45, v52, v53
	v_cvt_pk_bf16_f32 v26, v38, v39
	v_cvt_pk_bf16_f32 v27, v40, v41
	v_cvt_pk_bf16_f32 v28, v34, v35
	v_cvt_pk_bf16_f32 v29, v36, v37
	global_store_dwordx4 v[30:31], v[14:17], off offset:256
	v_cvt_pk_bf16_f32 v12, v18, v19
	v_cvt_pk_bf16_f32 v13, v20, v21
	v_lshl_add_u64 v[14:15], v[10:11], 0, v[144:145]
	v_cvt_pk_bf16_f32 v10, v22, v23
	v_cvt_pk_bf16_f32 v11, v24, v25
	v_cvt_pk_bf16_f32 v6, v6, v7
	v_cvt_pk_bf16_f32 v7, v8, v9
	v_cvt_pk_bf16_f32 v8, v2, v3
	v_cvt_pk_bf16_f32 v9, v4, v5
	s_and_b64 vcc, exec, s[40:41]
	s_mov_b32 s60, s0
	s_mov_b32 s61, s38
	s_mov_b64 s[48:49], s[44:45]
	s_mov_b64 s[46:47], s[42:43]
	global_store_dwordx4 v[148:149], v[126:129], off
	global_store_dwordx4 v[110:111], v[106:109], off
	global_store_dwordx4 v[94:95], v[90:93], off
	global_store_dwordx4 v[78:79], v[74:77], off
	global_store_dwordx4 v[78:79], v[70:73], off offset:256
	global_store_dwordx4 v[66:67], v[62:65], off
	global_store_dwordx4 v[46:47], v[42:45], off
	global_store_dwordx4 v[30:31], v[26:29], off
	global_store_dwordx4 v[14:15], v[10:13], off
	global_store_dwordx4 v[14:15], v[6:9], off offset:256
	s_cbranch_vccz .LBB0_227
	s_waitcnt vmcnt(0)
	v_readlane_b32 s60, v255, 21
	s_cmpk_gt_u32 s36, 0xff
	s_mov_b32 s18, s60
	v_readlane_b32 s61, v255, 22
	s_cbranch_scc1 .LBB0_238
	s_barrier

.LBB0_282:
	s_add_i32 s67, s50, 2
	s_add_u32 s51, s0, 0xfff80080
	s_addc_u32 s52, s1, -1
	s_add_i32 s68, 0, 0x10000
	v_add_u32_e32 v148, s68, v153
	ds_read_b128 v[136:139], v148
	ds_read_b128 v[140:143], v148 offset:1024
	ds_read_b128 v[144:147], v148 offset:2048
	ds_read_b128 v[148:151], v148 offset:3072
	s_cmp_eq_u32 s12, s50
	s_cselect_b32 s50, s48, s13
	s_cselect_b32 s53, s47, s52
	s_cselect_b32 s52, s46, s51
	s_cselect_b32 s51, s49, s66
	s_add_i32 m0, s55, 0xc000
	ds_read_b128 v[168:171], v155
	ds_read_b128 v[172:175], v155 offset:1024
	ds_read_b128 v[176:179], v155 offset:2048
	ds_read_b128 v[180:183], v155 offset:3072
	ds_read_b128 v[184:187], v155 offset:4096
	ds_read_b128 v[188:191], v155 offset:5120
	ds_read_b128 v[192:195], v155 offset:6144
	ds_read_b128 v[196:199], v155 offset:7168
	global_load_lds_dwordx4 v132, s[0:1]
	s_add_i32 m0, s55, 0xe000
	s_nop 0
	global_load_lds_dwordx4 v134, s[0:1]
	s_waitcnt lgkmcnt(8)
	s_barrier
	s_waitcnt lgkmcnt(0)
	v_mfma_f32_16x16x32_bf16 v[126:129], v[136:139], v[168:171], v[126:129]
	v_mfma_f32_16x16x32_bf16 v[122:125], v[144:147], v[168:171], v[122:125]
	v_mfma_f32_16x16x32_bf16 v[110:113], v[136:139], v[176:179], v[110:113]
	v_mfma_f32_16x16x32_bf16 v[106:109], v[144:147], v[176:179], v[106:109]
	v_mfma_f32_16x16x32_bf16 v[94:97], v[136:139], v[184:187], v[94:97]
	v_mfma_f32_16x16x32_bf16 v[90:93], v[144:147], v[184:187], v[90:93]
	v_mfma_f32_16x16x32_bf16 v[78:81], v[136:139], v[192:195], v[78:81]
	v_mfma_f32_16x16x32_bf16 v[74:77], v[144:147], v[192:195], v[74:77]
	v_mfma_f32_16x16x32_bf16 v[126:129], v[140:143], v[172:175], v[126:129]
	v_mfma_f32_16x16x32_bf16 v[122:125], v[148:151], v[172:175], v[122:125]
	v_mfma_f32_16x16x32_bf16 v[110:113], v[140:143], v[180:183], v[110:113]
	v_mfma_f32_16x16x32_bf16 v[106:109], v[148:151], v[180:183], v[106:109]
	v_mfma_f32_16x16x32_bf16 v[94:97], v[140:143], v[188:191], v[94:97]
	v_mfma_f32_16x16x32_bf16 v[90:93], v[148:151], v[188:191], v[90:93]
	v_mfma_f32_16x16x32_bf16 v[78:81], v[140:143], v[196:199], v[78:81]
	v_mfma_f32_16x16x32_bf16 v[74:77], v[148:151], v[196:199], v[74:77]
	s_barrier
	s_add_i32 s70, 0, 0x14000
	v_add_u32_e32 v156, s70, v153
	s_add_i32 s68, s68, s54
	ds_read_b128 v[224:227], v156
	ds_read_b128 v[228:231], v156 offset:1024
	ds_read_b128 v[232:235], v156 offset:2048
	ds_read_b128 v[236:239], v156 offset:3072
	s_add_u32 s76, s50, s94
	s_addc_u32 s77, s51, s95
	s_mov_b32 m0, s68
	s_nop 0
	global_load_lds_dwordx4 v0, s[50:51]
	s_add_i32 m0, s68, 0x2000
	s_nop 0
	global_load_lds_dwordx4 v130, s[50:51]
	s_barrier
	s_waitcnt lgkmcnt(0)
	v_mfma_f32_16x16x32_bf16 v[118:121], v[224:227], v[168:171], v[118:121]
	v_mfma_f32_16x16x32_bf16 v[114:117], v[232:235], v[168:171], v[114:117]
	v_mfma_f32_16x16x32_bf16 v[102:105], v[224:227], v[176:179], v[102:105]
	v_mfma_f32_16x16x32_bf16 v[98:101], v[232:235], v[176:179], v[98:101]
	v_mfma_f32_16x16x32_bf16 v[86:89], v[224:227], v[184:187], v[86:89]
	v_mfma_f32_16x16x32_bf16 v[82:85], v[232:235], v[184:187], v[82:85]
	v_mfma_f32_16x16x32_bf16 v[70:73], v[224:227], v[192:195], v[70:73]
	v_mfma_f32_16x16x32_bf16 v[66:69], v[232:235], v[192:195], v[66:69]
	v_mfma_f32_16x16x32_bf16 v[118:121], v[228:231], v[172:175], v[118:121]
	v_mfma_f32_16x16x32_bf16 v[114:117], v[236:239], v[172:175], v[114:117]
	v_mfma_f32_16x16x32_bf16 v[102:105], v[228:231], v[180:183], v[102:105]
	v_mfma_f32_16x16x32_bf16 v[98:101], v[236:239], v[180:183], v[98:101]
	v_mfma_f32_16x16x32_bf16 v[86:89], v[228:231], v[188:191], v[86:89]
	v_mfma_f32_16x16x32_bf16 v[82:85], v[236:239], v[188:191], v[82:85]
	v_mfma_f32_16x16x32_bf16 v[70:73], v[228:231], v[196:199], v[70:73]
	v_mfma_f32_16x16x32_bf16 v[66:69], v[236:239], v[196:199], v[66:69]
	s_barrier
	s_mov_b32 m0, s55
	s_add_u32 s78, s52, s94
	s_addc_u32 s79, s53, s95
	ds_read_b128 v[168:171], v155 offset:16384
	ds_read_b128 v[172:175], v155 offset:17408
	ds_read_b128 v[176:179], v155 offset:18432
	ds_read_b128 v[180:183], v155 offset:19456
	ds_read_b128 v[184:187], v155 offset:20480
	ds_read_b128 v[188:191], v155 offset:21504
	ds_read_b128 v[192:195], v155 offset:22528
	ds_read_b128 v[196:199], v155 offset:23552
	global_load_lds_dwordx4 v0, s[52:53]
	s_mov_b32 m0, s56
	s_nop 0
	global_load_lds_dwordx4 v130, s[52:53]
	s_barrier
	s_waitcnt lgkmcnt(0)
	v_mfma_f32_16x16x32_bf16 v[62:65], v[136:139], v[168:171], v[62:65]
	v_mfma_f32_16x16x32_bf16 v[58:61], v[144:147], v[168:171], v[58:61]
	v_mfma_f32_16x16x32_bf16 v[46:49], v[136:139], v[176:179], v[46:49]
	v_mfma_f32_16x16x32_bf16 v[42:45], v[144:147], v[176:179], v[42:45]
	v_mfma_f32_16x16x32_bf16 v[30:33], v[136:139], v[184:187], v[30:33]
	v_mfma_f32_16x16x32_bf16 v[26:29], v[144:147], v[184:187], v[26:29]
	v_mfma_f32_16x16x32_bf16 v[14:17], v[136:139], v[192:195], v[14:17]
	v_mfma_f32_16x16x32_bf16 v[10:13], v[144:147], v[192:195], v[10:13]
	v_mfma_f32_16x16x32_bf16 v[62:65], v[140:143], v[172:175], v[62:65]
	v_mfma_f32_16x16x32_bf16 v[58:61], v[148:151], v[172:175], v[58:61]
	v_mfma_f32_16x16x32_bf16 v[46:49], v[140:143], v[180:183], v[46:49]
	v_mfma_f32_16x16x32_bf16 v[42:45], v[148:151], v[180:183], v[42:45]
	v_mfma_f32_16x16x32_bf16 v[30:33], v[140:143], v[188:191], v[30:33]
	v_mfma_f32_16x16x32_bf16 v[26:29], v[148:151], v[188:191], v[26:29]
	v_mfma_f32_16x16x32_bf16 v[14:17], v[140:143], v[196:199], v[14:17]
	v_mfma_f32_16x16x32_bf16 v[10:13], v[148:151], v[196:199], v[10:13]
	s_barrier
	s_add_u32 s68, s50, 0x80000
	s_addc_u32 s69, s51, 0
	s_add_i32 s70, s70, s54
	s_mov_b32 m0, s70
	s_nop 0
	global_load_lds_dwordx4 v0, s[68:69]
	s_add_i32 m0, s70, 0x2000
	s_nop 0
	global_load_lds_dwordx4 v130, s[68:69]
	s_waitcnt vmcnt(6)
	s_barrier
	v_mfma_f32_16x16x32_bf16 v[54:57], v[224:227], v[168:171], v[54:57]
	v_mfma_f32_16x16x32_bf16 v[50:53], v[232:235], v[168:171], v[50:53]
	v_mfma_f32_16x16x32_bf16 v[38:41], v[224:227], v[176:179], v[38:41]
	v_mfma_f32_16x16x32_bf16 v[34:37], v[232:235], v[176:179], v[34:37]
	v_mfma_f32_16x16x32_bf16 v[22:25], v[224:227], v[184:187], v[22:25]
	v_mfma_f32_16x16x32_bf16 v[18:21], v[232:235], v[184:187], v[18:21]
	v_mfma_f32_16x16x32_bf16 v[6:9], v[224:227], v[192:195], v[6:9]
	v_mfma_f32_16x16x32_bf16 v[2:5], v[232:235], v[192:195], v[2:5]
	v_mfma_f32_16x16x32_bf16 v[54:57], v[228:231], v[172:175], v[54:57]
	v_mfma_f32_16x16x32_bf16 v[50:53], v[236:239], v[172:175], v[50:53]
	v_mfma_f32_16x16x32_bf16 v[38:41], v[228:231], v[180:183], v[38:41]
	v_mfma_f32_16x16x32_bf16 v[34:37], v[236:239], v[180:183], v[34:37]
	v_mfma_f32_16x16x32_bf16 v[22:25], v[228:231], v[188:191], v[22:25]
	v_mfma_f32_16x16x32_bf16 v[18:21], v[236:239], v[188:191], v[18:21]
	v_mfma_f32_16x16x32_bf16 v[6:9], v[228:231], v[196:199], v[6:9]
	v_mfma_f32_16x16x32_bf16 v[2:5], v[236:239], v[196:199], v[2:5]
	s_barrier
	s_add_i32 s68, 0, 0x18000
	v_add_u32_e32 v148, s68, v153
	ds_read_b128 v[136:139], v148
	ds_read_b128 v[140:143], v148 offset:1024
	ds_read_b128 v[144:147], v148 offset:2048
	ds_read_b128 v[148:151], v148 offset:3072
	s_add_u32 s52, s52, 0x80000
	s_addc_u32 s53, s53, 0
	s_mov_b32 m0, s57
	ds_read_b128 v[168:171], v155 offset:32768
	ds_read_b128 v[172:175], v155 offset:33792
	ds_read_b128 v[176:179], v155 offset:34816
	ds_read_b128 v[180:183], v155 offset:35840
	ds_read_b128 v[184:187], v155 offset:36864
	ds_read_b128 v[188:191], v155 offset:37888
	ds_read_b128 v[192:195], v155 offset:38912
	ds_read_b128 v[196:199], v155 offset:39936
	global_load_lds_dwordx4 v0, s[52:53]
	s_mov_b32 m0, s58
	s_nop 0
	global_load_lds_dwordx4 v130, s[52:53]
	s_waitcnt lgkmcnt(8)
	s_barrier
	s_waitcnt lgkmcnt(0)
	v_mfma_f32_16x16x32_bf16 v[126:129], v[136:139], v[168:171], v[126:129]
	v_mfma_f32_16x16x32_bf16 v[122:125], v[144:147], v[168:171], v[122:125]
	v_mfma_f32_16x16x32_bf16 v[110:113], v[136:139], v[176:179], v[110:113]
	v_mfma_f32_16x16x32_bf16 v[106:109], v[144:147], v[176:179], v[106:109]
	v_mfma_f32_16x16x32_bf16 v[94:97], v[136:139], v[184:187], v[94:97]
	v_mfma_f32_16x16x32_bf16 v[90:93], v[144:147], v[184:187], v[90:93]
	v_mfma_f32_16x16x32_bf16 v[78:81], v[136:139], v[192:195], v[78:81]
	v_mfma_f32_16x16x32_bf16 v[74:77], v[144:147], v[192:195], v[74:77]
	v_mfma_f32_16x16x32_bf16 v[126:129], v[140:143], v[172:175], v[126:129]
	v_mfma_f32_16x16x32_bf16 v[122:125], v[148:151], v[172:175], v[122:125]
	v_mfma_f32_16x16x32_bf16 v[110:113], v[140:143], v[180:183], v[110:113]
	v_mfma_f32_16x16x32_bf16 v[106:109], v[148:151], v[180:183], v[106:109]
	v_mfma_f32_16x16x32_bf16 v[94:97], v[140:143], v[188:191], v[94:97]
	v_mfma_f32_16x16x32_bf16 v[90:93], v[148:151], v[188:191], v[90:93]
	v_mfma_f32_16x16x32_bf16 v[78:81], v[140:143], v[196:199], v[78:81]
	v_mfma_f32_16x16x32_bf16 v[74:77], v[148:151], v[196:199], v[74:77]
	s_barrier
	s_add_i32 s52, 0, 0x1c000
	s_add_i32 s53, s68, s54
	v_add_u32_e32 v161, s52, v153
	s_mov_b32 m0, s53
	ds_read_b128 v[224:227], v161
	ds_read_b128 v[228:231], v161 offset:1024
	ds_read_b128 v[232:235], v161 offset:2048
	ds_read_b128 v[236:239], v161 offset:3072
	global_load_lds_dwordx4 v0, s[76:77]
	s_add_i32 m0, s53, 0x2000
	s_nop 0
	global_load_lds_dwordx4 v130, s[76:77]
	s_barrier
	s_waitcnt lgkmcnt(0)
	v_mfma_f32_16x16x32_bf16 v[118:121], v[224:227], v[168:171], v[118:121]
	v_mfma_f32_16x16x32_bf16 v[114:117], v[232:235], v[168:171], v[114:117]
	v_mfma_f32_16x16x32_bf16 v[102:105], v[224:227], v[176:179], v[102:105]
	v_mfma_f32_16x16x32_bf16 v[98:101], v[232:235], v[176:179], v[98:101]
	v_mfma_f32_16x16x32_bf16 v[86:89], v[224:227], v[184:187], v[86:89]
	v_mfma_f32_16x16x32_bf16 v[82:85], v[232:235], v[184:187], v[82:85]
	v_mfma_f32_16x16x32_bf16 v[70:73], v[224:227], v[192:195], v[70:73]
	v_mfma_f32_16x16x32_bf16 v[66:69], v[232:235], v[192:195], v[66:69]
	v_mfma_f32_16x16x32_bf16 v[118:121], v[228:231], v[172:175], v[118:121]
	v_mfma_f32_16x16x32_bf16 v[114:117], v[236:239], v[172:175], v[114:117]
	v_mfma_f32_16x16x32_bf16 v[102:105], v[228:231], v[180:183], v[102:105]
	v_mfma_f32_16x16x32_bf16 v[98:101], v[236:239], v[180:183], v[98:101]
	v_mfma_f32_16x16x32_bf16 v[86:89], v[228:231], v[188:191], v[86:89]
	v_mfma_f32_16x16x32_bf16 v[82:85], v[236:239], v[188:191], v[82:85]
	v_mfma_f32_16x16x32_bf16 v[70:73], v[228:231], v[196:199], v[70:73]
	v_mfma_f32_16x16x32_bf16 v[66:69], v[236:239], v[196:199], v[66:69]
	s_barrier
	s_mov_b32 m0, s59
	ds_read_b128 v[168:171], v155 offset:49152
	ds_read_b128 v[172:175], v155 offset:50176
	ds_read_b128 v[176:179], v155 offset:51200
	ds_read_b128 v[180:183], v155 offset:52224
	ds_read_b128 v[184:187], v155 offset:53248
	ds_read_b128 v[188:191], v155 offset:54272
	ds_read_b128 v[192:195], v155 offset:55296
	ds_read_b128 v[196:199], v155 offset:56320
	global_load_lds_dwordx4 v0, s[78:79]
	s_mov_b32 m0, s60
	s_nop 0
	global_load_lds_dwordx4 v130, s[78:79]
	s_barrier
	s_waitcnt lgkmcnt(0)
	v_mfma_f32_16x16x32_bf16 v[62:65], v[136:139], v[168:171], v[62:65]
	v_mfma_f32_16x16x32_bf16 v[58:61], v[144:147], v[168:171], v[58:61]
	v_mfma_f32_16x16x32_bf16 v[46:49], v[136:139], v[176:179], v[46:49]
	v_mfma_f32_16x16x32_bf16 v[42:45], v[144:147], v[176:179], v[42:45]
	v_mfma_f32_16x16x32_bf16 v[30:33], v[136:139], v[184:187], v[30:33]
	v_mfma_f32_16x16x32_bf16 v[26:29], v[144:147], v[184:187], v[26:29]
	v_mfma_f32_16x16x32_bf16 v[14:17], v[136:139], v[192:195], v[14:17]
	v_mfma_f32_16x16x32_bf16 v[10:13], v[144:147], v[192:195], v[10:13]
	v_mfma_f32_16x16x32_bf16 v[62:65], v[140:143], v[172:175], v[62:65]
	v_mfma_f32_16x16x32_bf16 v[58:61], v[148:151], v[172:175], v[58:61]
	v_mfma_f32_16x16x32_bf16 v[46:49], v[140:143], v[180:183], v[46:49]
	v_mfma_f32_16x16x32_bf16 v[42:45], v[148:151], v[180:183], v[42:45]
	v_mfma_f32_16x16x32_bf16 v[30:33], v[140:143], v[188:191], v[30:33]
	v_mfma_f32_16x16x32_bf16 v[26:29], v[148:151], v[188:191], v[26:29]
	v_mfma_f32_16x16x32_bf16 v[14:17], v[140:143], v[196:199], v[14:17]
	v_mfma_f32_16x16x32_bf16 v[10:13], v[148:151], v[196:199], v[10:13]
	s_barrier
	s_add_u32 s50, s50, 0x80080
	s_addc_u32 s51, s51, 0
	s_add_i32 s52, s52, s54
	s_mov_b32 m0, s52
	s_nop 0
	global_load_lds_dwordx4 v0, s[50:51]
	s_add_i32 m0, s52, 0x2000
	s_nop 0
	global_load_lds_dwordx4 v130, s[50:51]
	s_waitcnt vmcnt(6)
	s_barrier
	v_mfma_f32_16x16x32_bf16 v[54:57], v[224:227], v[168:171], v[54:57]
	v_mfma_f32_16x16x32_bf16 v[50:53], v[232:235], v[168:171], v[50:53]
	v_mfma_f32_16x16x32_bf16 v[38:41], v[224:227], v[176:179], v[38:41]
	v_mfma_f32_16x16x32_bf16 v[34:37], v[232:235], v[176:179], v[34:37]
	v_mfma_f32_16x16x32_bf16 v[22:25], v[224:227], v[184:187], v[22:25]
	v_mfma_f32_16x16x32_bf16 v[18:21], v[232:235], v[184:187], v[18:21]
	v_mfma_f32_16x16x32_bf16 v[6:9], v[224:227], v[192:195], v[6:9]
	v_mfma_f32_16x16x32_bf16 v[2:5], v[232:235], v[192:195], v[2:5]
	v_mfma_f32_16x16x32_bf16 v[54:57], v[228:231], v[172:175], v[54:57]
	v_mfma_f32_16x16x32_bf16 v[50:53], v[236:239], v[172:175], v[50:53]
	v_mfma_f32_16x16x32_bf16 v[38:41], v[228:231], v[180:183], v[38:41]
	v_mfma_f32_16x16x32_bf16 v[34:37], v[236:239], v[180:183], v[34:37]
	v_mfma_f32_16x16x32_bf16 v[22:25], v[228:231], v[188:191], v[22:25]
	v_mfma_f32_16x16x32_bf16 v[18:21], v[236:239], v[188:191], v[18:21]
	v_mfma_f32_16x16x32_bf16 v[6:9], v[228:231], v[196:199], v[6:9]
	v_mfma_f32_16x16x32_bf16 v[2:5], v[236:239], v[196:199], v[2:5]
	s_barrier
	s_add_u32 s0, s0, 0x100
	s_addc_u32 s1, s1, 0
	s_add_u32 s13, s13, 0x100
	s_addc_u32 s66, s66, 0
	s_cmp_ge_i32 s67, s41
	s_mov_b32 s50, s67
	s_cbranch_scc0 .LBB0_282
	s_cmp_eq_u32 s63, 2
	s_cbranch_scc1 .Lepi6_orig
	v_readlane_b32 s90, v255, 17
	v_readlane_b32 s91, v255, 18
	v_readlane_b32 s96, v255, 19
	v_readlane_b32 s97, v255, 20
	v_readlane_b32 s8, v255, 25
	v_readlane_b32 s9, v255, 26
	v_readlane_b32 s68, v253, 58
	v_readlane_b32 s69, v253, 59
	v_lshl_or_b32 v156, s64, 8, v154
	v_lshlrev_b32_e32 v156, 2, v156
	v_lshl_add_u32 v157, v152, 13, v156
	s_lshl_b32 s72, s65, 21
	s_add_u32 s74, s68, s72
	s_addc_u32 s75, s69, 0
	s_add_u32 s76, s22, s72
	s_addc_u32 s77, s23, 0
	s_lshr_b32 s73, s65, 3
	s_mul_i32 s73, s73, 0xc000
	s_add_u32 s73, s73, 0x4000
	s_add_u32 s70, s90, s73
	s_addc_u32 s71, s91, 0
	global_load_dwordx4 v[140:143], v156, s[70:71]
	global_load_dwordx4 v[144:147], v156, s[70:71] offset:64
	global_load_dwordx4 v[148:151], v156, s[70:71] offset:512
	global_load_dwordx4 v[168:171], v156, s[70:71] offset:576
	global_load_dwordx4 v[224:227], v157, s[74:75] nt
	global_load_dwordx4 v[228:231], v157, s[74:75] offset:64 nt
	global_load_dwordx4 v[232:235], v157, s[74:75] offset:512 nt
	global_load_dwordx4 v[236:239], v157, s[74:75] offset:576 nt
	s_add_u32 s74, s74, 0x20000
	s_addc_u32 s75, s75, 0
	global_load_dwordx4 v[240:243], v157, s[74:75] nt
	global_load_dwordx4 v[244:247], v157, s[74:75] offset:64 nt
	s_waitcnt vmcnt(5)
	v_pk_fma_f32 v[128:129], v[128:129], v[142:143], v[226:227]
	v_pk_fma_f32 v[126:127], v[126:127], v[140:141], v[224:225]
	global_store_dwordx4 v157, v[126:129], s[76:77]
	global_load_dwordx4 v[224:227], v157, s[74:75] offset:512 nt
	s_waitcnt vmcnt(6)
	v_pk_fma_f32 v[124:125], v[124:125], v[146:147], v[230:231]
	v_pk_fma_f32 v[122:123], v[122:123], v[144:145], v[228:229]
	global_store_dwordx4 v157, v[122:125], s[76:77] offset:64
	global_load_dwordx4 v[228:231], v157, s[74:75] offset:576 nt
	s_waitcnt vmcnt(7)
	v_pk_fma_f32 v[120:121], v[120:121], v[150:151], v[234:235]
	v_pk_fma_f32 v[118:119], v[118:119], v[148:149], v[232:233]
	global_store_dwordx4 v157, v[118:121], s[76:77] offset:512
	s_add_u32 s74, s74, 0x20000
	s_addc_u32 s75, s75, 0
	global_load_dwordx4 v[232:235], v157, s[74:75] nt
	s_waitcnt vmcnt(8)
	v_pk_fma_f32 v[116:117], v[116:117], v[170:171], v[238:239]
	v_pk_fma_f32 v[114:115], v[114:115], v[168:169], v[236:237]
	global_store_dwordx4 v157, v[114:117], s[76:77] offset:576
	global_load_dwordx4 v[236:239], v157, s[74:75] offset:64 nt
	s_add_u32 s76, s76, 0x20000
	s_addc_u32 s77, s77, 0
	s_waitcnt vmcnt(9)
	v_pk_fma_f32 v[112:113], v[112:113], v[142:143], v[242:243]
	v_pk_fma_f32 v[110:111], v[110:111], v[140:141], v[240:241]
	global_store_dwordx4 v157, v[110:113], s[76:77]
	global_load_dwordx4 v[240:243], v157, s[74:75] offset:512 nt
	s_waitcnt vmcnt(10)
	v_pk_fma_f32 v[108:109], v[108:109], v[146:147], v[246:247]
	v_pk_fma_f32 v[106:107], v[106:107], v[144:145], v[244:245]
	global_store_dwordx4 v157, v[106:109], s[76:77] offset:64
	global_load_dwordx4 v[244:247], v157, s[74:75] offset:576 nt
	s_waitcnt vmcnt(10)
	v_pk_fma_f32 v[104:105], v[104:105], v[150:151], v[226:227]
	v_pk_fma_f32 v[102:103], v[102:103], v[148:149], v[224:225]
	global_store_dwordx4 v157, v[102:105], s[76:77] offset:512
	s_add_u32 s74, s74, 0x20000
	s_addc_u32 s75, s75, 0
	global_load_dwordx4 v[224:227], v157, s[74:75] nt
	s_waitcnt vmcnt(10)
	v_pk_fma_f32 v[100:101], v[100:101], v[170:171], v[230:231]
	v_pk_fma_f32 v[98:99], v[98:99], v[168:169], v[228:229]
	global_store_dwordx4 v157, v[98:101], s[76:77] offset:576
	global_load_dwordx4 v[228:231], v157, s[74:75] offset:64 nt
	s_add_u32 s76, s76, 0x20000
	s_addc_u32 s77, s77, 0
	s_waitcnt vmcnt(10)
	v_pk_fma_f32 v[96:97], v[96:97], v[142:143], v[234:235]
	v_pk_fma_f32 v[94:95], v[94:95], v[140:141], v[232:233]
	global_store_dwordx4 v157, v[94:97], s[76:77]
	global_load_dwordx4 v[232:235], v157, s[74:75] offset:512 nt
	s_waitcnt vmcnt(10)
	v_pk_fma_f32 v[92:93], v[92:93], v[146:147], v[238:239]
	v_pk_fma_f32 v[90:91], v[90:91], v[144:145], v[236:237]
	global_store_dwordx4 v157, v[90:93], s[76:77] offset:64
	global_load_dwordx4 v[236:239], v157, s[74:75] offset:576 nt
	s_waitcnt vmcnt(10)
	v_pk_fma_f32 v[88:89], v[88:89], v[150:151], v[242:243]
	v_pk_fma_f32 v[86:87], v[86:87], v[148:149], v[240:241]
	global_store_dwordx4 v157, v[86:89], s[76:77] offset:512
	s_add_u32 s74, s74, 0xa0000
	s_addc_u32 s75, s75, 0
	global_load_dwordx4 v[240:243], v157, s[74:75] nt
	s_waitcnt vmcnt(10)
	v_pk_fma_f32 v[84:85], v[84:85], v[170:171], v[246:247]
	v_pk_fma_f32 v[82:83], v[82:83], v[168:169], v[244:245]
	global_store_dwordx4 v157, v[82:85], s[76:77] offset:576
	global_load_dwordx4 v[244:247], v157, s[74:75] offset:64 nt
	s_add_u32 s76, s76, 0x20000
	s_addc_u32 s77, s77, 0
	s_waitcnt vmcnt(10)
	v_pk_fma_f32 v[80:81], v[80:81], v[142:143], v[226:227]
	v_pk_fma_f32 v[78:79], v[78:79], v[140:141], v[224:225]
	global_store_dwordx4 v157, v[78:81], s[76:77]
	global_load_dwordx4 v[224:227], v157, s[74:75] offset:512 nt
	s_waitcnt vmcnt(10)
	v_pk_fma_f32 v[76:77], v[76:77], v[146:147], v[230:231]
	v_pk_fma_f32 v[74:75], v[74:75], v[144:145], v[228:229]
	global_store_dwordx4 v157, v[74:77], s[76:77] offset:64
	global_load_dwordx4 v[228:231], v157, s[74:75] offset:576 nt
	s_waitcnt vmcnt(10)
	v_pk_fma_f32 v[72:73], v[72:73], v[150:151], v[234:235]
	v_pk_fma_f32 v[70:71], v[70:71], v[148:149], v[232:233]
	global_store_dwordx4 v157, v[70:73], s[76:77] offset:512
	s_add_u32 s74, s74, 0x20000
	s_addc_u32 s75, s75, 0
	global_load_dwordx4 v[232:235], v157, s[74:75] nt
	s_waitcnt vmcnt(10)
	v_pk_fma_f32 v[68:69], v[68:69], v[170:171], v[238:239]
	v_pk_fma_f32 v[66:67], v[66:67], v[168:169], v[236:237]
	global_store_dwordx4 v157, v[66:69], s[76:77] offset:576
	global_load_dwordx4 v[236:239], v157, s[74:75] offset:64 nt
	s_add_u32 s76, s76, 0xa0000
	s_addc_u32 s77, s77, 0
	s_waitcnt vmcnt(10)
	v_pk_fma_f32 v[64:65], v[64:65], v[142:143], v[242:243]
	v_pk_fma_f32 v[62:63], v[62:63], v[140:141], v[240:241]
	global_store_dwordx4 v157, v[62:65], s[76:77]
	global_load_dwordx4 v[240:243], v157, s[74:75] offset:512 nt
	s_waitcnt vmcnt(10)
	v_pk_fma_f32 v[60:61], v[60:61], v[146:147], v[246:247]
	v_pk_fma_f32 v[58:59], v[58:59], v[144:145], v[244:245]
	global_store_dwordx4 v157, v[58:61], s[76:77] offset:64
	global_load_dwordx4 v[244:247], v157, s[74:75] offset:576 nt
	s_waitcnt vmcnt(10)
	v_pk_fma_f32 v[56:57], v[56:57], v[150:151], v[226:227]
	v_pk_fma_f32 v[54:55], v[54:55], v[148:149], v[224:225]
	global_store_dwordx4 v157, v[54:57], s[76:77] offset:512
	s_add_u32 s74, s74, 0x20000
	s_addc_u32 s75, s75, 0
	global_load_dwordx4 v[224:227], v157, s[74:75] nt
	s_waitcnt vmcnt(10)
	v_pk_fma_f32 v[52:53], v[52:53], v[170:171], v[230:231]
	v_pk_fma_f32 v[50:51], v[50:51], v[168:169], v[228:229]
	global_store_dwordx4 v157, v[50:53], s[76:77] offset:576
	global_load_dwordx4 v[228:231], v157, s[74:75] offset:64 nt
	s_add_u32 s76, s76, 0x20000
	s_addc_u32 s77, s77, 0
	s_waitcnt vmcnt(10)
	v_pk_fma_f32 v[48:49], v[48:49], v[142:143], v[234:235]
	v_pk_fma_f32 v[46:47], v[46:47], v[140:141], v[232:233]
	global_store_dwordx4 v157, v[46:49], s[76:77]
	global_load_dwordx4 v[232:235], v157, s[74:75] offset:512 nt
	s_waitcnt vmcnt(10)
	v_pk_fma_f32 v[44:45], v[44:45], v[146:147], v[238:239]
	v_pk_fma_f32 v[42:43], v[42:43], v[144:145], v[236:237]
	global_store_dwordx4 v157, v[42:45], s[76:77] offset:64
	global_load_dwordx4 v[236:239], v157, s[74:75] offset:576 nt
	s_waitcnt vmcnt(10)
	v_pk_fma_f32 v[40:41], v[40:41], v[150:151], v[242:243]
	v_pk_fma_f32 v[38:39], v[38:39], v[148:149], v[240:241]
	global_store_dwordx4 v157, v[38:41], s[76:77] offset:512
	s_add_u32 s74, s74, 0x20000
	s_addc_u32 s75, s75, 0
	global_load_dwordx4 v[240:243], v157, s[74:75] nt
	s_waitcnt vmcnt(10)
	v_pk_fma_f32 v[36:37], v[36:37], v[170:171], v[246:247]
	v_pk_fma_f32 v[34:35], v[34:35], v[168:169], v[244:245]
	global_store_dwordx4 v157, v[34:37], s[76:77] offset:576
	global_load_dwordx4 v[244:247], v157, s[74:75] offset:64 nt
	s_add_u32 s76, s76, 0x20000
	s_addc_u32 s77, s77, 0
	s_waitcnt vmcnt(10)
	v_pk_fma_f32 v[32:33], v[32:33], v[142:143], v[226:227]
	v_pk_fma_f32 v[30:31], v[30:31], v[140:141], v[224:225]
	global_store_dwordx4 v157, v[30:33], s[76:77]
	global_load_dwordx4 v[224:227], v157, s[74:75] offset:512 nt
	s_waitcnt vmcnt(10)
	v_pk_fma_f32 v[28:29], v[28:29], v[146:147], v[230:231]
	v_pk_fma_f32 v[26:27], v[26:27], v[144:145], v[228:229]
	global_store_dwordx4 v157, v[26:29], s[76:77] offset:64
	global_load_dwordx4 v[228:231], v157, s[74:75] offset:576 nt
	s_waitcnt vmcnt(10)
	v_pk_fma_f32 v[24:25], v[24:25], v[150:151], v[234:235]
	v_pk_fma_f32 v[22:23], v[22:23], v[148:149], v[232:233]
	global_store_dwordx4 v157, v[22:25], s[76:77] offset:512
	s_waitcnt vmcnt(9)
	v_pk_fma_f32 v[20:21], v[20:21], v[170:171], v[238:239]
	v_pk_fma_f32 v[18:19], v[18:19], v[168:169], v[236:237]
	global_store_dwordx4 v157, v[18:21], s[76:77] offset:576
	s_add_u32 s76, s76, 0x20000
	s_addc_u32 s77, s77, 0
	s_waitcnt vmcnt(8)
	v_pk_fma_f32 v[16:17], v[16:17], v[142:143], v[242:243]
	v_pk_fma_f32 v[14:15], v[14:15], v[140:141], v[240:241]
	global_store_dwordx4 v157, v[14:17], s[76:77]
	s_waitcnt vmcnt(7)
	v_pk_fma_f32 v[12:13], v[12:13], v[146:147], v[246:247]
	v_pk_fma_f32 v[10:11], v[10:11], v[144:145], v[244:245]
	global_store_dwordx4 v157, v[10:13], s[76:77] offset:64
	s_waitcnt vmcnt(6)
	v_pk_fma_f32 v[8:9], v[8:9], v[150:151], v[226:227]
	v_pk_fma_f32 v[6:7], v[6:7], v[148:149], v[224:225]
	global_store_dwordx4 v157, v[6:9], s[76:77] offset:512
	s_waitcnt vmcnt(5)
	v_pk_fma_f32 v[4:5], v[4:5], v[170:171], v[230:231]
	v_pk_fma_f32 v[2:3], v[2:3], v[168:169], v[228:229]
	global_store_dwordx4 v157, v[2:5], s[76:77] offset:576
	s_branch .LBB0_269

.LBB0_572:
	s_add_u32 s41, s46, 0xfff80080
	s_addc_u32 s48, s47, -1
	s_add_i32 s64, 0, 0x10000
	v_add_u32_e32 v156, s64, v141
	ds_read_b128 v[144:147], v156
	ds_read_b128 v[148:151], v156 offset:1024
	ds_read_b128 v[152:155], v156 offset:2048
	ds_read_b128 v[168:171], v156 offset:3072
	s_cmp_eq_u32 s39, 28
	s_cselect_b32 s51, s43, s48
	s_cselect_b32 s50, s42, s41
	s_cselect_b32 s49, s45, s13
	s_cselect_b32 s48, s44, s12
	s_add_i32 m0, s54, 0xc000
	ds_read_b128 v[172:175], v143
	ds_read_b128 v[176:179], v143 offset:1024
	ds_read_b128 v[180:183], v143 offset:2048
	ds_read_b128 v[184:187], v143 offset:3072
	ds_read_b128 v[188:191], v143 offset:4096
	ds_read_b128 v[192:195], v143 offset:5120
	ds_read_b128 v[196:199], v143 offset:6144
	ds_read_b128 v[224:227], v143 offset:7168
	global_load_lds_dwordx4 v136, s[46:47]
	s_add_i32 m0, s54, 0xe000
	s_nop 0
	global_load_lds_dwordx4 v138, s[46:47]
	s_waitcnt lgkmcnt(8)
	s_barrier
	s_waitcnt lgkmcnt(0)
	v_mfma_f32_16x16x32_bf16 v[126:129], v[144:147], v[172:175], v[126:129]
	v_mfma_f32_16x16x32_bf16 v[122:125], v[152:155], v[172:175], v[122:125]
	v_mfma_f32_16x16x32_bf16 v[118:121], v[144:147], v[180:183], v[118:121]
	v_mfma_f32_16x16x32_bf16 v[114:117], v[152:155], v[180:183], v[114:117]
	v_mfma_f32_16x16x32_bf16 v[102:105], v[144:147], v[188:191], v[102:105]
	v_mfma_f32_16x16x32_bf16 v[98:101], v[152:155], v[188:191], v[98:101]
	v_mfma_f32_16x16x32_bf16 v[86:89], v[144:147], v[196:199], v[86:89]
	v_mfma_f32_16x16x32_bf16 v[82:85], v[152:155], v[196:199], v[82:85]
	v_mfma_f32_16x16x32_bf16 v[126:129], v[148:151], v[176:179], v[126:129]
	v_mfma_f32_16x16x32_bf16 v[122:125], v[168:171], v[176:179], v[122:125]
	v_mfma_f32_16x16x32_bf16 v[118:121], v[148:151], v[184:187], v[118:121]
	v_mfma_f32_16x16x32_bf16 v[114:117], v[168:171], v[184:187], v[114:117]
	v_mfma_f32_16x16x32_bf16 v[102:105], v[148:151], v[192:195], v[102:105]
	v_mfma_f32_16x16x32_bf16 v[98:101], v[168:171], v[192:195], v[98:101]
	v_mfma_f32_16x16x32_bf16 v[86:89], v[148:151], v[224:227], v[86:89]
	v_mfma_f32_16x16x32_bf16 v[82:85], v[168:171], v[224:227], v[82:85]
	s_barrier
	s_add_i32 s41, 0, 0x14000
	v_add_u32_e32 v156, s41, v141
	s_add_i32 s64, s64, s53
	ds_read_b128 v[228:231], v156
	ds_read_b128 v[232:235], v156 offset:1024
	ds_read_b128 v[236:239], v156 offset:2048
	ds_read_b128 v[240:243], v156 offset:3072
	s_add_u32 s76, s48, s94
	s_addc_u32 s77, s49, s95
	s_mov_b32 m0, s64
	s_nop 0
	global_load_lds_dwordx4 v0, s[48:49]
	s_add_i32 m0, s64, 0x2000
	s_nop 0
	global_load_lds_dwordx4 v134, s[48:49]
	s_barrier
	s_waitcnt lgkmcnt(0)
	v_mfma_f32_16x16x32_bf16 v[110:113], v[228:231], v[172:175], v[110:113]
	v_mfma_f32_16x16x32_bf16 v[106:109], v[236:239], v[172:175], v[106:109]
	v_mfma_f32_16x16x32_bf16 v[94:97], v[228:231], v[180:183], v[94:97]
	v_mfma_f32_16x16x32_bf16 v[90:93], v[236:239], v[180:183], v[90:93]
	v_mfma_f32_16x16x32_bf16 v[78:81], v[228:231], v[188:191], v[78:81]
	v_mfma_f32_16x16x32_bf16 v[74:77], v[236:239], v[188:191], v[74:77]
	v_mfma_f32_16x16x32_bf16 v[70:73], v[228:231], v[196:199], v[70:73]
	v_mfma_f32_16x16x32_bf16 v[66:69], v[236:239], v[196:199], v[66:69]
	v_mfma_f32_16x16x32_bf16 v[110:113], v[232:235], v[176:179], v[110:113]
	v_mfma_f32_16x16x32_bf16 v[106:109], v[240:243], v[176:179], v[106:109]
	v_mfma_f32_16x16x32_bf16 v[94:97], v[232:235], v[184:187], v[94:97]
	v_mfma_f32_16x16x32_bf16 v[90:93], v[240:243], v[184:187], v[90:93]
	v_mfma_f32_16x16x32_bf16 v[78:81], v[232:235], v[192:195], v[78:81]
	v_mfma_f32_16x16x32_bf16 v[74:77], v[240:243], v[192:195], v[74:77]
	v_mfma_f32_16x16x32_bf16 v[70:73], v[232:235], v[224:227], v[70:73]
	v_mfma_f32_16x16x32_bf16 v[66:69], v[240:243], v[224:227], v[66:69]
	s_barrier
	s_mov_b32 m0, s54
	s_add_u32 s78, s50, s94
	s_addc_u32 s79, s51, s95
	ds_read_b128 v[172:175], v143 offset:16384
	ds_read_b128 v[176:179], v143 offset:17408
	ds_read_b128 v[180:183], v143 offset:18432
	ds_read_b128 v[184:187], v143 offset:19456
	ds_read_b128 v[188:191], v143 offset:20480
	ds_read_b128 v[192:195], v143 offset:21504
	ds_read_b128 v[196:199], v143 offset:22528
	ds_read_b128 v[224:227], v143 offset:23552
	global_load_lds_dwordx4 v130, s[50:51]
	s_mov_b32 m0, s55
	s_nop 0
	global_load_lds_dwordx4 v132, s[50:51]
	s_barrier
	s_waitcnt lgkmcnt(0)
	v_mfma_f32_16x16x32_bf16 v[62:65], v[144:147], v[172:175], v[62:65]
	v_mfma_f32_16x16x32_bf16 v[58:61], v[152:155], v[172:175], v[58:61]
	v_mfma_f32_16x16x32_bf16 v[54:57], v[144:147], v[180:183], v[54:57]
	v_mfma_f32_16x16x32_bf16 v[50:53], v[152:155], v[180:183], v[50:53]
	v_mfma_f32_16x16x32_bf16 v[38:41], v[144:147], v[188:191], v[38:41]
	v_mfma_f32_16x16x32_bf16 v[34:37], v[152:155], v[188:191], v[34:37]
	v_mfma_f32_16x16x32_bf16 v[22:25], v[144:147], v[196:199], v[22:25]
	v_mfma_f32_16x16x32_bf16 v[18:21], v[152:155], v[196:199], v[18:21]
	v_mfma_f32_16x16x32_bf16 v[62:65], v[148:151], v[176:179], v[62:65]
	v_mfma_f32_16x16x32_bf16 v[58:61], v[168:171], v[176:179], v[58:61]
	v_mfma_f32_16x16x32_bf16 v[54:57], v[148:151], v[184:187], v[54:57]
	v_mfma_f32_16x16x32_bf16 v[50:53], v[168:171], v[184:187], v[50:53]
	v_mfma_f32_16x16x32_bf16 v[38:41], v[148:151], v[192:195], v[38:41]
	v_mfma_f32_16x16x32_bf16 v[34:37], v[168:171], v[192:195], v[34:37]
	v_mfma_f32_16x16x32_bf16 v[22:25], v[148:151], v[224:227], v[22:25]
	v_mfma_f32_16x16x32_bf16 v[18:21], v[168:171], v[224:227], v[18:21]
	s_barrier
	s_add_u32 s64, s48, 0x80000
	s_addc_u32 s65, s49, 0
	s_add_i32 s41, s41, s53
	s_mov_b32 m0, s41
	s_nop 0
	global_load_lds_dwordx4 v0, s[64:65]
	s_add_i32 m0, s41, 0x2000
	s_nop 0
	global_load_lds_dwordx4 v134, s[64:65]
	s_waitcnt vmcnt(6)
	s_barrier
	v_mfma_f32_16x16x32_bf16 v[46:49], v[228:231], v[172:175], v[46:49]
	v_mfma_f32_16x16x32_bf16 v[42:45], v[236:239], v[172:175], v[42:45]
	v_mfma_f32_16x16x32_bf16 v[30:33], v[228:231], v[180:183], v[30:33]
	v_mfma_f32_16x16x32_bf16 v[26:29], v[236:239], v[180:183], v[26:29]
	v_mfma_f32_16x16x32_bf16 v[14:17], v[228:231], v[188:191], v[14:17]
	v_mfma_f32_16x16x32_bf16 v[10:13], v[236:239], v[188:191], v[10:13]
	v_mfma_f32_16x16x32_bf16 v[6:9], v[228:231], v[196:199], v[6:9]
	v_mfma_f32_16x16x32_bf16 v[2:5], v[236:239], v[196:199], v[2:5]
	v_mfma_f32_16x16x32_bf16 v[46:49], v[232:235], v[176:179], v[46:49]
	v_mfma_f32_16x16x32_bf16 v[42:45], v[240:243], v[176:179], v[42:45]
	v_mfma_f32_16x16x32_bf16 v[30:33], v[232:235], v[184:187], v[30:33]
	v_mfma_f32_16x16x32_bf16 v[26:29], v[240:243], v[184:187], v[26:29]
	v_mfma_f32_16x16x32_bf16 v[14:17], v[232:235], v[192:195], v[14:17]
	v_mfma_f32_16x16x32_bf16 v[10:13], v[240:243], v[192:195], v[10:13]
	v_mfma_f32_16x16x32_bf16 v[6:9], v[232:235], v[224:227], v[6:9]
	v_mfma_f32_16x16x32_bf16 v[2:5], v[240:243], v[224:227], v[2:5]
	s_barrier
	s_add_i32 s41, 0, 0x18000
	v_add_u32_e32 v161, s41, v141
	ds_read_b128 v[144:147], v161
	ds_read_b128 v[148:151], v161 offset:1024
	ds_read_b128 v[152:155], v161 offset:2048
	ds_read_b128 v[168:171], v161 offset:3072
	s_add_u32 s50, s50, 0x80000
	s_addc_u32 s51, s51, 0
	s_mov_b32 m0, s56
	ds_read_b128 v[172:175], v143 offset:32768
	ds_read_b128 v[176:179], v143 offset:33792
	ds_read_b128 v[180:183], v143 offset:34816
	ds_read_b128 v[184:187], v143 offset:35840
	ds_read_b128 v[188:191], v143 offset:36864
	ds_read_b128 v[192:195], v143 offset:37888
	ds_read_b128 v[196:199], v143 offset:38912
	ds_read_b128 v[224:227], v143 offset:39936
	global_load_lds_dwordx4 v130, s[50:51]
	s_mov_b32 m0, s57
	s_nop 0
	global_load_lds_dwordx4 v132, s[50:51]
	s_waitcnt lgkmcnt(8)
	s_barrier
	s_waitcnt lgkmcnt(0)
	v_mfma_f32_16x16x32_bf16 v[126:129], v[144:147], v[172:175], v[126:129]
	v_mfma_f32_16x16x32_bf16 v[122:125], v[152:155], v[172:175], v[122:125]
	v_mfma_f32_16x16x32_bf16 v[118:121], v[144:147], v[180:183], v[118:121]
	v_mfma_f32_16x16x32_bf16 v[114:117], v[152:155], v[180:183], v[114:117]
	v_mfma_f32_16x16x32_bf16 v[102:105], v[144:147], v[188:191], v[102:105]
	v_mfma_f32_16x16x32_bf16 v[98:101], v[152:155], v[188:191], v[98:101]
	v_mfma_f32_16x16x32_bf16 v[86:89], v[144:147], v[196:199], v[86:89]
	v_mfma_f32_16x16x32_bf16 v[82:85], v[152:155], v[196:199], v[82:85]
	v_mfma_f32_16x16x32_bf16 v[126:129], v[148:151], v[176:179], v[126:129]
	v_mfma_f32_16x16x32_bf16 v[122:125], v[168:171], v[176:179], v[122:125]
	v_mfma_f32_16x16x32_bf16 v[118:121], v[148:151], v[184:187], v[118:121]
	v_mfma_f32_16x16x32_bf16 v[114:117], v[168:171], v[184:187], v[114:117]
	v_mfma_f32_16x16x32_bf16 v[102:105], v[148:151], v[192:195], v[102:105]
	v_mfma_f32_16x16x32_bf16 v[98:101], v[168:171], v[192:195], v[98:101]
	v_mfma_f32_16x16x32_bf16 v[86:89], v[148:151], v[224:227], v[86:89]
	v_mfma_f32_16x16x32_bf16 v[82:85], v[168:171], v[224:227], v[82:85]
	s_barrier
	s_add_i32 s50, 0, 0x1c000
	s_add_i32 s41, s41, s53
	v_add_u32_e32 v161, s50, v141
	s_mov_b32 m0, s41
	ds_read_b128 v[228:231], v161
	ds_read_b128 v[232:235], v161 offset:1024
	ds_read_b128 v[236:239], v161 offset:2048
	ds_read_b128 v[240:243], v161 offset:3072
	global_load_lds_dwordx4 v0, s[76:77]
	s_add_i32 m0, s41, 0x2000
	s_nop 0
	global_load_lds_dwordx4 v134, s[76:77]
	s_barrier
	s_waitcnt lgkmcnt(0)
	v_mfma_f32_16x16x32_bf16 v[110:113], v[228:231], v[172:175], v[110:113]
	v_mfma_f32_16x16x32_bf16 v[106:109], v[236:239], v[172:175], v[106:109]
	v_mfma_f32_16x16x32_bf16 v[94:97], v[228:231], v[180:183], v[94:97]
	v_mfma_f32_16x16x32_bf16 v[90:93], v[236:239], v[180:183], v[90:93]
	v_mfma_f32_16x16x32_bf16 v[78:81], v[228:231], v[188:191], v[78:81]
	v_mfma_f32_16x16x32_bf16 v[74:77], v[236:239], v[188:191], v[74:77]
	v_mfma_f32_16x16x32_bf16 v[70:73], v[228:231], v[196:199], v[70:73]
	v_mfma_f32_16x16x32_bf16 v[66:69], v[236:239], v[196:199], v[66:69]
	v_mfma_f32_16x16x32_bf16 v[110:113], v[232:235], v[176:179], v[110:113]
	v_mfma_f32_16x16x32_bf16 v[106:109], v[240:243], v[176:179], v[106:109]
	v_mfma_f32_16x16x32_bf16 v[94:97], v[232:235], v[184:187], v[94:97]
	v_mfma_f32_16x16x32_bf16 v[90:93], v[240:243], v[184:187], v[90:93]
	v_mfma_f32_16x16x32_bf16 v[78:81], v[232:235], v[192:195], v[78:81]
	v_mfma_f32_16x16x32_bf16 v[74:77], v[240:243], v[192:195], v[74:77]
	v_mfma_f32_16x16x32_bf16 v[70:73], v[232:235], v[224:227], v[70:73]
	v_mfma_f32_16x16x32_bf16 v[66:69], v[240:243], v[224:227], v[66:69]
	s_barrier
	s_mov_b32 m0, s59
	ds_read_b128 v[172:175], v143 offset:49152
	ds_read_b128 v[176:179], v143 offset:50176
	ds_read_b128 v[180:183], v143 offset:51200
	ds_read_b128 v[184:187], v143 offset:52224
	ds_read_b128 v[188:191], v143 offset:53248
	ds_read_b128 v[192:195], v143 offset:54272
	ds_read_b128 v[196:199], v143 offset:55296
	ds_read_b128 v[224:227], v143 offset:56320
	global_load_lds_dwordx4 v130, s[78:79]
	s_mov_b32 m0, s60
	s_nop 0
	global_load_lds_dwordx4 v132, s[78:79]
	s_barrier
	s_waitcnt lgkmcnt(0)
	v_mfma_f32_16x16x32_bf16 v[62:65], v[144:147], v[172:175], v[62:65]
	v_mfma_f32_16x16x32_bf16 v[58:61], v[152:155], v[172:175], v[58:61]
	v_mfma_f32_16x16x32_bf16 v[54:57], v[144:147], v[180:183], v[54:57]
	v_mfma_f32_16x16x32_bf16 v[50:53], v[152:155], v[180:183], v[50:53]
	v_mfma_f32_16x16x32_bf16 v[38:41], v[144:147], v[188:191], v[38:41]
	v_mfma_f32_16x16x32_bf16 v[34:37], v[152:155], v[188:191], v[34:37]
	v_mfma_f32_16x16x32_bf16 v[22:25], v[144:147], v[196:199], v[22:25]
	v_mfma_f32_16x16x32_bf16 v[18:21], v[152:155], v[196:199], v[18:21]
	v_mfma_f32_16x16x32_bf16 v[62:65], v[148:151], v[176:179], v[62:65]
	v_mfma_f32_16x16x32_bf16 v[58:61], v[168:171], v[176:179], v[58:61]
	v_mfma_f32_16x16x32_bf16 v[54:57], v[148:151], v[184:187], v[54:57]
	v_mfma_f32_16x16x32_bf16 v[50:53], v[168:171], v[184:187], v[50:53]
	v_mfma_f32_16x16x32_bf16 v[38:41], v[148:151], v[192:195], v[38:41]
	v_mfma_f32_16x16x32_bf16 v[34:37], v[168:171], v[192:195], v[34:37]
	v_mfma_f32_16x16x32_bf16 v[22:25], v[148:151], v[224:227], v[22:25]
	v_mfma_f32_16x16x32_bf16 v[18:21], v[168:171], v[224:227], v[18:21]
	s_barrier
	s_add_u32 s48, s48, 0x80080
	s_addc_u32 s49, s49, 0
	s_add_i32 s41, s50, s53
	s_mov_b32 m0, s41
	s_nop 0
	global_load_lds_dwordx4 v0, s[48:49]
	s_add_i32 m0, s41, 0x2000
	s_nop 0
	global_load_lds_dwordx4 v134, s[48:49]
	s_waitcnt vmcnt(6)
	s_barrier
	v_mfma_f32_16x16x32_bf16 v[46:49], v[228:231], v[172:175], v[46:49]
	v_mfma_f32_16x16x32_bf16 v[42:45], v[236:239], v[172:175], v[42:45]
	v_mfma_f32_16x16x32_bf16 v[30:33], v[228:231], v[180:183], v[30:33]
	v_mfma_f32_16x16x32_bf16 v[26:29], v[236:239], v[180:183], v[26:29]
	v_mfma_f32_16x16x32_bf16 v[14:17], v[228:231], v[188:191], v[14:17]
	v_mfma_f32_16x16x32_bf16 v[10:13], v[236:239], v[188:191], v[10:13]
	v_mfma_f32_16x16x32_bf16 v[6:9], v[228:231], v[196:199], v[6:9]
	v_mfma_f32_16x16x32_bf16 v[2:5], v[236:239], v[196:199], v[2:5]
	v_mfma_f32_16x16x32_bf16 v[46:49], v[232:235], v[176:179], v[46:49]
	v_mfma_f32_16x16x32_bf16 v[42:45], v[240:243], v[176:179], v[42:45]
	v_mfma_f32_16x16x32_bf16 v[30:33], v[232:235], v[184:187], v[30:33]
	v_mfma_f32_16x16x32_bf16 v[26:29], v[240:243], v[184:187], v[26:29]
	v_mfma_f32_16x16x32_bf16 v[14:17], v[232:235], v[192:195], v[14:17]
	v_mfma_f32_16x16x32_bf16 v[10:13], v[240:243], v[192:195], v[10:13]
	v_mfma_f32_16x16x32_bf16 v[6:9], v[232:235], v[224:227], v[6:9]
	v_mfma_f32_16x16x32_bf16 v[2:5], v[240:243], v[224:227], v[2:5]
	s_barrier
	s_add_i32 s39, s39, 2
	s_add_u32 s46, s46, 0x100
	s_addc_u32 s47, s47, 0
	s_add_u32 s12, s12, 0x100
	s_addc_u32 s13, s13, 0
	s_cmp_gt_u32 s39, 29
	s_cbranch_scc0 .LBB0_572
	s_cmp_lg_u32 s62, 0
	s_cbranch_scc0 .LBB0_575
	s_lshl_b32 s39, s61, 8
	s_mov_b64 s[12:13], 0
	s_branch .LBB0_576

.LBB0_788:
	s_add_u32 s39, s46, 0xfff80080
	s_addc_u32 s48, s47, -1
	s_add_i32 s64, 0, 0x10000
	v_add_u32_e32 v156, s64, v141
	ds_read_b128 v[144:147], v156
	ds_read_b128 v[148:151], v156 offset:1024
	ds_read_b128 v[152:155], v156 offset:2048
	ds_read_b128 v[168:171], v156 offset:3072
	s_cmp_eq_u32 s13, 28
	s_cselect_b32 s51, s43, s48
	s_cselect_b32 s50, s42, s39
	s_cselect_b32 s49, s45, s12
	s_cselect_b32 s48, s44, s1
	s_add_i32 m0, s54, 0xc000
	ds_read_b128 v[172:175], v143
	ds_read_b128 v[176:179], v143 offset:1024
	ds_read_b128 v[180:183], v143 offset:2048
	ds_read_b128 v[184:187], v143 offset:3072
	ds_read_b128 v[188:191], v143 offset:4096
	ds_read_b128 v[192:195], v143 offset:5120
	ds_read_b128 v[196:199], v143 offset:6144
	ds_read_b128 v[224:227], v143 offset:7168
	global_load_lds_dwordx4 v136, s[46:47]
	s_add_i32 m0, s54, 0xe000
	s_nop 0
	global_load_lds_dwordx4 v138, s[46:47]
	s_waitcnt lgkmcnt(8)
	s_barrier
	s_waitcnt lgkmcnt(0)
	v_mfma_f32_16x16x32_bf16 v[126:129], v[144:147], v[172:175], v[126:129]
	v_mfma_f32_16x16x32_bf16 v[122:125], v[152:155], v[172:175], v[122:125]
	v_mfma_f32_16x16x32_bf16 v[118:121], v[144:147], v[180:183], v[118:121]
	v_mfma_f32_16x16x32_bf16 v[114:117], v[152:155], v[180:183], v[114:117]
	v_mfma_f32_16x16x32_bf16 v[102:105], v[144:147], v[188:191], v[102:105]
	v_mfma_f32_16x16x32_bf16 v[98:101], v[152:155], v[188:191], v[98:101]
	v_mfma_f32_16x16x32_bf16 v[86:89], v[144:147], v[196:199], v[86:89]
	v_mfma_f32_16x16x32_bf16 v[82:85], v[152:155], v[196:199], v[82:85]
	v_mfma_f32_16x16x32_bf16 v[126:129], v[148:151], v[176:179], v[126:129]
	v_mfma_f32_16x16x32_bf16 v[122:125], v[168:171], v[176:179], v[122:125]
	v_mfma_f32_16x16x32_bf16 v[118:121], v[148:151], v[184:187], v[118:121]
	v_mfma_f32_16x16x32_bf16 v[114:117], v[168:171], v[184:187], v[114:117]
	v_mfma_f32_16x16x32_bf16 v[102:105], v[148:151], v[192:195], v[102:105]
	v_mfma_f32_16x16x32_bf16 v[98:101], v[168:171], v[192:195], v[98:101]
	v_mfma_f32_16x16x32_bf16 v[86:89], v[148:151], v[224:227], v[86:89]
	v_mfma_f32_16x16x32_bf16 v[82:85], v[168:171], v[224:227], v[82:85]
	s_barrier
	s_add_i32 s39, 0, 0x14000
	v_add_u32_e32 v156, s39, v141
	s_add_i32 s64, s64, s53
	ds_read_b128 v[228:231], v156
	ds_read_b128 v[232:235], v156 offset:1024
	ds_read_b128 v[236:239], v156 offset:2048
	ds_read_b128 v[240:243], v156 offset:3072
	s_add_u32 s76, s48, s94
	s_addc_u32 s77, s49, s95
	s_mov_b32 m0, s64
	s_nop 0
	global_load_lds_dwordx4 v0, s[48:49]
	s_add_i32 m0, s64, 0x2000
	s_nop 0
	global_load_lds_dwordx4 v134, s[48:49]
	s_barrier
	s_waitcnt lgkmcnt(0)
	v_mfma_f32_16x16x32_bf16 v[110:113], v[228:231], v[172:175], v[110:113]
	v_mfma_f32_16x16x32_bf16 v[106:109], v[236:239], v[172:175], v[106:109]
	v_mfma_f32_16x16x32_bf16 v[94:97], v[228:231], v[180:183], v[94:97]
	v_mfma_f32_16x16x32_bf16 v[90:93], v[236:239], v[180:183], v[90:93]
	v_mfma_f32_16x16x32_bf16 v[78:81], v[228:231], v[188:191], v[78:81]
	v_mfma_f32_16x16x32_bf16 v[74:77], v[236:239], v[188:191], v[74:77]
	v_mfma_f32_16x16x32_bf16 v[70:73], v[228:231], v[196:199], v[70:73]
	v_mfma_f32_16x16x32_bf16 v[66:69], v[236:239], v[196:199], v[66:69]
	v_mfma_f32_16x16x32_bf16 v[110:113], v[232:235], v[176:179], v[110:113]
	v_mfma_f32_16x16x32_bf16 v[106:109], v[240:243], v[176:179], v[106:109]
	v_mfma_f32_16x16x32_bf16 v[94:97], v[232:235], v[184:187], v[94:97]
	v_mfma_f32_16x16x32_bf16 v[90:93], v[240:243], v[184:187], v[90:93]
	v_mfma_f32_16x16x32_bf16 v[78:81], v[232:235], v[192:195], v[78:81]
	v_mfma_f32_16x16x32_bf16 v[74:77], v[240:243], v[192:195], v[74:77]
	v_mfma_f32_16x16x32_bf16 v[70:73], v[232:235], v[224:227], v[70:73]
	v_mfma_f32_16x16x32_bf16 v[66:69], v[240:243], v[224:227], v[66:69]
	s_barrier
	s_mov_b32 m0, s54
	s_add_u32 s78, s50, s94
	s_addc_u32 s79, s51, s95
	ds_read_b128 v[172:175], v143 offset:16384
	ds_read_b128 v[176:179], v143 offset:17408
	ds_read_b128 v[180:183], v143 offset:18432
	ds_read_b128 v[184:187], v143 offset:19456
	ds_read_b128 v[188:191], v143 offset:20480
	ds_read_b128 v[192:195], v143 offset:21504
	ds_read_b128 v[196:199], v143 offset:22528
	ds_read_b128 v[224:227], v143 offset:23552
	global_load_lds_dwordx4 v130, s[50:51]
	s_mov_b32 m0, s55
	s_nop 0
	global_load_lds_dwordx4 v132, s[50:51]
	s_barrier
	s_waitcnt lgkmcnt(0)
	v_mfma_f32_16x16x32_bf16 v[62:65], v[144:147], v[172:175], v[62:65]
	v_mfma_f32_16x16x32_bf16 v[58:61], v[152:155], v[172:175], v[58:61]
	v_mfma_f32_16x16x32_bf16 v[54:57], v[144:147], v[180:183], v[54:57]
	v_mfma_f32_16x16x32_bf16 v[50:53], v[152:155], v[180:183], v[50:53]
	v_mfma_f32_16x16x32_bf16 v[38:41], v[144:147], v[188:191], v[38:41]
	v_mfma_f32_16x16x32_bf16 v[34:37], v[152:155], v[188:191], v[34:37]
	v_mfma_f32_16x16x32_bf16 v[22:25], v[144:147], v[196:199], v[22:25]
	v_mfma_f32_16x16x32_bf16 v[18:21], v[152:155], v[196:199], v[18:21]
	v_mfma_f32_16x16x32_bf16 v[62:65], v[148:151], v[176:179], v[62:65]
	v_mfma_f32_16x16x32_bf16 v[58:61], v[168:171], v[176:179], v[58:61]
	v_mfma_f32_16x16x32_bf16 v[54:57], v[148:151], v[184:187], v[54:57]
	v_mfma_f32_16x16x32_bf16 v[50:53], v[168:171], v[184:187], v[50:53]
	v_mfma_f32_16x16x32_bf16 v[38:41], v[148:151], v[192:195], v[38:41]
	v_mfma_f32_16x16x32_bf16 v[34:37], v[168:171], v[192:195], v[34:37]
	v_mfma_f32_16x16x32_bf16 v[22:25], v[148:151], v[224:227], v[22:25]
	v_mfma_f32_16x16x32_bf16 v[18:21], v[168:171], v[224:227], v[18:21]
	s_barrier
	s_add_u32 s64, s48, 0x80000
	s_addc_u32 s65, s49, 0
	s_add_i32 s39, s39, s53
	s_mov_b32 m0, s39
	s_nop 0
	global_load_lds_dwordx4 v0, s[64:65]
	s_add_i32 m0, s39, 0x2000
	s_nop 0
	global_load_lds_dwordx4 v134, s[64:65]
	s_waitcnt vmcnt(6)
	s_barrier
	v_mfma_f32_16x16x32_bf16 v[46:49], v[228:231], v[172:175], v[46:49]
	v_mfma_f32_16x16x32_bf16 v[42:45], v[236:239], v[172:175], v[42:45]
	v_mfma_f32_16x16x32_bf16 v[30:33], v[228:231], v[180:183], v[30:33]
	v_mfma_f32_16x16x32_bf16 v[26:29], v[236:239], v[180:183], v[26:29]
	v_mfma_f32_16x16x32_bf16 v[14:17], v[228:231], v[188:191], v[14:17]
	v_mfma_f32_16x16x32_bf16 v[10:13], v[236:239], v[188:191], v[10:13]
	v_mfma_f32_16x16x32_bf16 v[6:9], v[228:231], v[196:199], v[6:9]
	v_mfma_f32_16x16x32_bf16 v[2:5], v[236:239], v[196:199], v[2:5]
	v_mfma_f32_16x16x32_bf16 v[46:49], v[232:235], v[176:179], v[46:49]
	v_mfma_f32_16x16x32_bf16 v[42:45], v[240:243], v[176:179], v[42:45]
	v_mfma_f32_16x16x32_bf16 v[30:33], v[232:235], v[184:187], v[30:33]
	v_mfma_f32_16x16x32_bf16 v[26:29], v[240:243], v[184:187], v[26:29]
	v_mfma_f32_16x16x32_bf16 v[14:17], v[232:235], v[192:195], v[14:17]
	v_mfma_f32_16x16x32_bf16 v[10:13], v[240:243], v[192:195], v[10:13]
	v_mfma_f32_16x16x32_bf16 v[6:9], v[232:235], v[224:227], v[6:9]
	v_mfma_f32_16x16x32_bf16 v[2:5], v[240:243], v[224:227], v[2:5]
	s_barrier
	s_add_i32 s39, 0, 0x18000
	v_add_u32_e32 v161, s39, v141
	ds_read_b128 v[144:147], v161
	ds_read_b128 v[148:151], v161 offset:1024
	ds_read_b128 v[152:155], v161 offset:2048
	ds_read_b128 v[168:171], v161 offset:3072
	s_add_u32 s50, s50, 0x80000
	s_addc_u32 s51, s51, 0
	s_mov_b32 m0, s56
	ds_read_b128 v[172:175], v143 offset:32768
	ds_read_b128 v[176:179], v143 offset:33792
	ds_read_b128 v[180:183], v143 offset:34816
	ds_read_b128 v[184:187], v143 offset:35840
	ds_read_b128 v[188:191], v143 offset:36864
	ds_read_b128 v[192:195], v143 offset:37888
	ds_read_b128 v[196:199], v143 offset:38912
	ds_read_b128 v[224:227], v143 offset:39936
	global_load_lds_dwordx4 v130, s[50:51]
	s_mov_b32 m0, s57
	s_nop 0
	global_load_lds_dwordx4 v132, s[50:51]
	s_waitcnt lgkmcnt(8)
	s_barrier
	s_waitcnt lgkmcnt(0)
	v_mfma_f32_16x16x32_bf16 v[126:129], v[144:147], v[172:175], v[126:129]
	v_mfma_f32_16x16x32_bf16 v[122:125], v[152:155], v[172:175], v[122:125]
	v_mfma_f32_16x16x32_bf16 v[118:121], v[144:147], v[180:183], v[118:121]
	v_mfma_f32_16x16x32_bf16 v[114:117], v[152:155], v[180:183], v[114:117]
	v_mfma_f32_16x16x32_bf16 v[102:105], v[144:147], v[188:191], v[102:105]
	v_mfma_f32_16x16x32_bf16 v[98:101], v[152:155], v[188:191], v[98:101]
	v_mfma_f32_16x16x32_bf16 v[86:89], v[144:147], v[196:199], v[86:89]
	v_mfma_f32_16x16x32_bf16 v[82:85], v[152:155], v[196:199], v[82:85]
	v_mfma_f32_16x16x32_bf16 v[126:129], v[148:151], v[176:179], v[126:129]
	v_mfma_f32_16x16x32_bf16 v[122:125], v[168:171], v[176:179], v[122:125]
	v_mfma_f32_16x16x32_bf16 v[118:121], v[148:151], v[184:187], v[118:121]
	v_mfma_f32_16x16x32_bf16 v[114:117], v[168:171], v[184:187], v[114:117]
	v_mfma_f32_16x16x32_bf16 v[102:105], v[148:151], v[192:195], v[102:105]
	v_mfma_f32_16x16x32_bf16 v[98:101], v[168:171], v[192:195], v[98:101]
	v_mfma_f32_16x16x32_bf16 v[86:89], v[148:151], v[224:227], v[86:89]
	v_mfma_f32_16x16x32_bf16 v[82:85], v[168:171], v[224:227], v[82:85]
	s_barrier
	s_add_i32 s50, 0, 0x1c000
	s_add_i32 s39, s39, s53
	v_add_u32_e32 v161, s50, v141
	s_mov_b32 m0, s39
	ds_read_b128 v[228:231], v161
	ds_read_b128 v[232:235], v161 offset:1024
	ds_read_b128 v[236:239], v161 offset:2048
	ds_read_b128 v[240:243], v161 offset:3072
	global_load_lds_dwordx4 v0, s[76:77]
	s_add_i32 m0, s39, 0x2000
	s_nop 0
	global_load_lds_dwordx4 v134, s[76:77]
	s_barrier
	s_waitcnt lgkmcnt(0)
	v_mfma_f32_16x16x32_bf16 v[110:113], v[228:231], v[172:175], v[110:113]
	v_mfma_f32_16x16x32_bf16 v[106:109], v[236:239], v[172:175], v[106:109]
	v_mfma_f32_16x16x32_bf16 v[94:97], v[228:231], v[180:183], v[94:97]
	v_mfma_f32_16x16x32_bf16 v[90:93], v[236:239], v[180:183], v[90:93]
	v_mfma_f32_16x16x32_bf16 v[78:81], v[228:231], v[188:191], v[78:81]
	v_mfma_f32_16x16x32_bf16 v[74:77], v[236:239], v[188:191], v[74:77]
	v_mfma_f32_16x16x32_bf16 v[70:73], v[228:231], v[196:199], v[70:73]
	v_mfma_f32_16x16x32_bf16 v[66:69], v[236:239], v[196:199], v[66:69]
	v_mfma_f32_16x16x32_bf16 v[110:113], v[232:235], v[176:179], v[110:113]
	v_mfma_f32_16x16x32_bf16 v[106:109], v[240:243], v[176:179], v[106:109]
	v_mfma_f32_16x16x32_bf16 v[94:97], v[232:235], v[184:187], v[94:97]
	v_mfma_f32_16x16x32_bf16 v[90:93], v[240:243], v[184:187], v[90:93]
	v_mfma_f32_16x16x32_bf16 v[78:81], v[232:235], v[192:195], v[78:81]
	v_mfma_f32_16x16x32_bf16 v[74:77], v[240:243], v[192:195], v[74:77]
	v_mfma_f32_16x16x32_bf16 v[70:73], v[232:235], v[224:227], v[70:73]
	v_mfma_f32_16x16x32_bf16 v[66:69], v[240:243], v[224:227], v[66:69]
	s_barrier
	s_mov_b32 m0, s59
	ds_read_b128 v[172:175], v143 offset:49152
	ds_read_b128 v[176:179], v143 offset:50176
	ds_read_b128 v[180:183], v143 offset:51200
	ds_read_b128 v[184:187], v143 offset:52224
	ds_read_b128 v[188:191], v143 offset:53248
	ds_read_b128 v[192:195], v143 offset:54272
	ds_read_b128 v[196:199], v143 offset:55296
	ds_read_b128 v[224:227], v143 offset:56320
	global_load_lds_dwordx4 v130, s[78:79]
	s_mov_b32 m0, s61
	s_nop 0
	global_load_lds_dwordx4 v132, s[78:79]
	s_barrier
	s_waitcnt lgkmcnt(0)
	v_mfma_f32_16x16x32_bf16 v[62:65], v[144:147], v[172:175], v[62:65]
	v_mfma_f32_16x16x32_bf16 v[58:61], v[152:155], v[172:175], v[58:61]
	v_mfma_f32_16x16x32_bf16 v[54:57], v[144:147], v[180:183], v[54:57]
	v_mfma_f32_16x16x32_bf16 v[50:53], v[152:155], v[180:183], v[50:53]
	v_mfma_f32_16x16x32_bf16 v[38:41], v[144:147], v[188:191], v[38:41]
	v_mfma_f32_16x16x32_bf16 v[34:37], v[152:155], v[188:191], v[34:37]
	v_mfma_f32_16x16x32_bf16 v[22:25], v[144:147], v[196:199], v[22:25]
	v_mfma_f32_16x16x32_bf16 v[18:21], v[152:155], v[196:199], v[18:21]
	v_mfma_f32_16x16x32_bf16 v[62:65], v[148:151], v[176:179], v[62:65]
	v_mfma_f32_16x16x32_bf16 v[58:61], v[168:171], v[176:179], v[58:61]
	v_mfma_f32_16x16x32_bf16 v[54:57], v[148:151], v[184:187], v[54:57]
	v_mfma_f32_16x16x32_bf16 v[50:53], v[168:171], v[184:187], v[50:53]
	v_mfma_f32_16x16x32_bf16 v[38:41], v[148:151], v[192:195], v[38:41]
	v_mfma_f32_16x16x32_bf16 v[34:37], v[168:171], v[192:195], v[34:37]
	v_mfma_f32_16x16x32_bf16 v[22:25], v[148:151], v[224:227], v[22:25]
	v_mfma_f32_16x16x32_bf16 v[18:21], v[168:171], v[224:227], v[18:21]
	s_barrier
	s_add_u32 s48, s48, 0x80080
	s_addc_u32 s49, s49, 0
	s_add_i32 s39, s50, s53
	s_mov_b32 m0, s39
	s_nop 0
	global_load_lds_dwordx4 v0, s[48:49]
	s_add_i32 m0, s39, 0x2000
	s_nop 0
	global_load_lds_dwordx4 v134, s[48:49]
	s_waitcnt vmcnt(6)
	s_barrier
	v_mfma_f32_16x16x32_bf16 v[46:49], v[228:231], v[172:175], v[46:49]
	v_mfma_f32_16x16x32_bf16 v[42:45], v[236:239], v[172:175], v[42:45]
	v_mfma_f32_16x16x32_bf16 v[30:33], v[228:231], v[180:183], v[30:33]
	v_mfma_f32_16x16x32_bf16 v[26:29], v[236:239], v[180:183], v[26:29]
	v_mfma_f32_16x16x32_bf16 v[14:17], v[228:231], v[188:191], v[14:17]
	v_mfma_f32_16x16x32_bf16 v[10:13], v[236:239], v[188:191], v[10:13]
	v_mfma_f32_16x16x32_bf16 v[6:9], v[228:231], v[196:199], v[6:9]
	v_mfma_f32_16x16x32_bf16 v[2:5], v[236:239], v[196:199], v[2:5]
	v_mfma_f32_16x16x32_bf16 v[46:49], v[232:235], v[176:179], v[46:49]
	v_mfma_f32_16x16x32_bf16 v[42:45], v[240:243], v[176:179], v[42:45]
	v_mfma_f32_16x16x32_bf16 v[30:33], v[232:235], v[184:187], v[30:33]
	v_mfma_f32_16x16x32_bf16 v[26:29], v[240:243], v[184:187], v[26:29]
	v_mfma_f32_16x16x32_bf16 v[14:17], v[232:235], v[192:195], v[14:17]
	v_mfma_f32_16x16x32_bf16 v[10:13], v[240:243], v[192:195], v[10:13]
	v_mfma_f32_16x16x32_bf16 v[6:9], v[232:235], v[224:227], v[6:9]
	v_mfma_f32_16x16x32_bf16 v[2:5], v[240:243], v[224:227], v[2:5]
	s_barrier
	s_add_i32 s13, s13, 2
	s_add_u32 s46, s46, 0x100
	s_addc_u32 s47, s47, 0
	s_add_u32 s1, s1, 0x100
	s_addc_u32 s12, s12, 0
	s_cmp_gt_u32 s13, 29
	s_cbranch_scc0 .LBB0_788
	s_cmp_lg_u32 s62, 0
	s_cbranch_scc0 .LBB0_791
	s_lshl_b32 s1, s60, 8
	s_mov_b64 s[12:13], 0
	s_branch .LBB0_792
